# weight conversion wcomb loops (both inlined copies) turned into straight-line code with loads two trips ahead and counted vmcnt
# speedup vs baseline: 1.0169x; 1.0032x over previous
; __device__ __forceinline__ void wcomb_item(const float* w_in, const float* wg, const float* ngain, bf16_t* WinT, int item, int lane) {
;     ...
;     const float* ap = w_in + (size_t)k * DIN + 128 * g; const float* bp = wg + (size_t)g * 128 * 128 + d0;
;     f32x4 c0 = (f32x4){0.f, 0.f, 0.f, 0.f}, c1 = c0;
; #pragma unroll 4
;     for (int cin = 0; cin < 128; ++cin) { const float av = ap[cin]; const f32x4 b0 = *(const f32x4*)(bp + (size_t)cin * 128), b1 = *(const f32x4*)(bp + (size_t)cin * 128 + 4); c0 += b0 * av; c1 += b1 * av; }
.LBB0_733:
	global_load_dwordx4 v[80:83], v[34:35], off offset:-8
	v_lshl_add_u64 v[116:117], v[32:33], 0, s[22:23]
	global_load_dwordx4 v[84:87], v[116:117], off
	global_load_dwordx4 v[88:91], v[116:117], off offset:16
	global_load_dwordx4 v[92:95], v[116:117], off offset:512
	global_load_dwordx4 v[96:99], v[116:117], off offset:528
	global_load_dwordx4 v[100:103], v[116:117], off offset:1024
	global_load_dwordx4 v[104:107], v[116:117], off offset:1040
	global_load_dwordx4 v[108:111], v[116:117], off offset:1536
	global_load_dwordx4 v[112:115], v[116:117], off offset:1552
	s_add_u32 s22, s22, 0x800
	s_addc_u32 s23, s23, 0
	v_lshl_add_u64 v[34:35], v[34:35], 0, 16
	global_load_dwordx4 v[144:147], v[34:35], off offset:-8
	v_lshl_add_u64 v[116:117], v[32:33], 0, s[22:23]
	global_load_dwordx4 v[148:151], v[116:117], off
	global_load_dwordx4 v[152:155], v[116:117], off offset:16
	global_load_dwordx4 v[156:159], v[116:117], off offset:512
	global_load_dwordx4 v[160:163], v[116:117], off offset:528
	global_load_dwordx4 v[164:167], v[116:117], off offset:1024
	global_load_dwordx4 v[168:171], v[116:117], off offset:1040
	global_load_dwordx4 v[172:175], v[116:117], off offset:1536
	global_load_dwordx4 v[176:179], v[116:117], off offset:1552
	s_add_u32 s22, s22, 0x800
	s_addc_u32 s23, s23, 0
	v_lshl_add_u64 v[34:35], v[34:35], 0, 16
	global_load_dwordx4 v[180:183], v[34:35], off offset:-8
	v_lshl_add_u64 v[116:117], v[32:33], 0, s[22:23]
	global_load_dwordx4 v[184:187], v[116:117], off
	global_load_dwordx4 v[188:191], v[116:117], off offset:16
	global_load_dwordx4 v[192:195], v[116:117], off offset:512
	global_load_dwordx4 v[196:199], v[116:117], off offset:528
	global_load_dwordx4 v[200:203], v[116:117], off offset:1024
	global_load_dwordx4 v[204:207], v[116:117], off offset:1040
	global_load_dwordx4 v[208:211], v[116:117], off offset:1536
	global_load_dwordx4 v[212:215], v[116:117], off offset:1552
	s_add_u32 s22, s22, 0x800
	s_addc_u32 s23, s23, 0
	v_lshl_add_u64 v[34:35], v[34:35], 0, 16
	s_waitcnt vmcnt(18)
	v_pk_fma_f32 v[36:37], v[84:85], v[80:81], v[36:37] op_sel_hi:[1,0,1]
	v_pk_fma_f32 v[30:31], v[86:87], v[80:81], v[30:31] op_sel_hi:[1,0,1]
	v_pk_fma_f32 v[38:39], v[88:89], v[80:81], v[38:39] op_sel_hi:[1,0,1]
	v_pk_fma_f32 v[28:29], v[90:91], v[80:81], v[28:29] op_sel_hi:[1,0,1]
	v_pk_fma_f32 v[36:37], v[92:93], v[80:81], v[36:37] op_sel:[0,1,0]
	v_pk_fma_f32 v[30:31], v[94:95], v[80:81], v[30:31] op_sel:[0,1,0]
	v_pk_fma_f32 v[38:39], v[96:97], v[80:81], v[38:39] op_sel:[0,1,0]
	v_pk_fma_f32 v[28:29], v[98:99], v[80:81], v[28:29] op_sel:[0,1,0]
	v_pk_fma_f32 v[36:37], v[100:101], v[82:83], v[36:37] op_sel_hi:[1,0,1]
	v_pk_fma_f32 v[30:31], v[102:103], v[82:83], v[30:31] op_sel_hi:[1,0,1]
	v_pk_fma_f32 v[38:39], v[104:105], v[82:83], v[38:39] op_sel_hi:[1,0,1]
	v_pk_fma_f32 v[28:29], v[106:107], v[82:83], v[28:29] op_sel_hi:[1,0,1]
	v_pk_fma_f32 v[36:37], v[108:109], v[82:83], v[36:37] op_sel:[0,1,0]
	v_pk_fma_f32 v[30:31], v[110:111], v[82:83], v[30:31] op_sel:[0,1,0]
	v_pk_fma_f32 v[38:39], v[112:113], v[82:83], v[38:39] op_sel:[0,1,0]
	v_pk_fma_f32 v[28:29], v[114:115], v[82:83], v[28:29] op_sel:[0,1,0]
	global_load_dwordx4 v[80:83], v[34:35], off offset:-8
	v_lshl_add_u64 v[116:117], v[32:33], 0, s[22:23]
	global_load_dwordx4 v[84:87], v[116:117], off
	global_load_dwordx4 v[88:91], v[116:117], off offset:16
	global_load_dwordx4 v[92:95], v[116:117], off offset:512
	global_load_dwordx4 v[96:99], v[116:117], off offset:528
	global_load_dwordx4 v[100:103], v[116:117], off offset:1024
	global_load_dwordx4 v[104:107], v[116:117], off offset:1040
	global_load_dwordx4 v[108:111], v[116:117], off offset:1536
	global_load_dwordx4 v[112:115], v[116:117], off offset:1552
	s_add_u32 s22, s22, 0x800
	s_addc_u32 s23, s23, 0
	v_lshl_add_u64 v[34:35], v[34:35], 0, 16
	s_waitcnt vmcnt(18)
	v_pk_fma_f32 v[36:37], v[148:149], v[144:145], v[36:37] op_sel_hi:[1,0,1]
	v_pk_fma_f32 v[30:31], v[150:151], v[144:145], v[30:31] op_sel_hi:[1,0,1]
	v_pk_fma_f32 v[38:39], v[152:153], v[144:145], v[38:39] op_sel_hi:[1,0,1]
	v_pk_fma_f32 v[28:29], v[154:155], v[144:145], v[28:29] op_sel_hi:[1,0,1]
	v_pk_fma_f32 v[36:37], v[156:157], v[144:145], v[36:37] op_sel:[0,1,0]
	v_pk_fma_f32 v[30:31], v[158:159], v[144:145], v[30:31] op_sel:[0,1,0]
	v_pk_fma_f32 v[38:39], v[160:161], v[144:145], v[38:39] op_sel:[0,1,0]
	v_pk_fma_f32 v[28:29], v[162:163], v[144:145], v[28:29] op_sel:[0,1,0]
	v_pk_fma_f32 v[36:37], v[164:165], v[146:147], v[36:37] op_sel_hi:[1,0,1]
	v_pk_fma_f32 v[30:31], v[166:167], v[146:147], v[30:31] op_sel_hi:[1,0,1]
	v_pk_fma_f32 v[38:39], v[168:169], v[146:147], v[38:39] op_sel_hi:[1,0,1]
	v_pk_fma_f32 v[28:29], v[170:171], v[146:147], v[28:29] op_sel_hi:[1,0,1]
	v_pk_fma_f32 v[36:37], v[172:173], v[146:147], v[36:37] op_sel:[0,1,0]
	v_pk_fma_f32 v[30:31], v[174:175], v[146:147], v[30:31] op_sel:[0,1,0]
	v_pk_fma_f32 v[38:39], v[176:177], v[146:147], v[38:39] op_sel:[0,1,0]
	v_pk_fma_f32 v[28:29], v[178:179], v[146:147], v[28:29] op_sel:[0,1,0]
	global_load_dwordx4 v[144:147], v[34:35], off offset:-8
	v_lshl_add_u64 v[116:117], v[32:33], 0, s[22:23]
	global_load_dwordx4 v[148:151], v[116:117], off
	global_load_dwordx4 v[152:155], v[116:117], off offset:16
	global_load_dwordx4 v[156:159], v[116:117], off offset:512
	global_load_dwordx4 v[160:163], v[116:117], off offset:528
	global_load_dwordx4 v[164:167], v[116:117], off offset:1024
	global_load_dwordx4 v[168:171], v[116:117], off offset:1040
	global_load_dwordx4 v[172:175], v[116:117], off offset:1536
	global_load_dwordx4 v[176:179], v[116:117], off offset:1552
	s_add_u32 s22, s22, 0x800
	s_addc_u32 s23, s23, 0
	v_lshl_add_u64 v[34:35], v[34:35], 0, 16
	s_waitcnt vmcnt(18)
; __device__ __forceinline__ void wcomb_item(const float* w_in, const float* wg, const float* ngain, bf16_t* WinT, int item, int lane) {
;     ...
; #pragma unroll 4
;     for (int cin = 0; cin < 128; ++cin) { const float av = ap[cin]; const f32x4 b0 = *(const f32x4*)(bp + (size_t)cin * 128), b1 = *(const f32x4*)(bp + (size_t)cin * 128 + 4); c0 += b0 * av; c1 += b1 * av; }
	v_pk_fma_f32 v[36:37], v[184:185], v[180:181], v[36:37] op_sel_hi:[1,0,1]
	v_pk_fma_f32 v[30:31], v[186:187], v[180:181], v[30:31] op_sel_hi:[1,0,1]
	v_pk_fma_f32 v[38:39], v[188:189], v[180:181], v[38:39] op_sel_hi:[1,0,1]
	v_pk_fma_f32 v[28:29], v[190:191], v[180:181], v[28:29] op_sel_hi:[1,0,1]
	v_pk_fma_f32 v[36:37], v[192:193], v[180:181], v[36:37] op_sel:[0,1,0]
	v_pk_fma_f32 v[30:31], v[194:195], v[180:181], v[30:31] op_sel:[0,1,0]
	v_pk_fma_f32 v[38:39], v[196:197], v[180:181], v[38:39] op_sel:[0,1,0]
	v_pk_fma_f32 v[28:29], v[198:199], v[180:181], v[28:29] op_sel:[0,1,0]
	v_pk_fma_f32 v[36:37], v[200:201], v[182:183], v[36:37] op_sel_hi:[1,0,1]
	v_pk_fma_f32 v[30:31], v[202:203], v[182:183], v[30:31] op_sel_hi:[1,0,1]
	v_pk_fma_f32 v[38:39], v[204:205], v[182:183], v[38:39] op_sel_hi:[1,0,1]
	v_pk_fma_f32 v[28:29], v[206:207], v[182:183], v[28:29] op_sel_hi:[1,0,1]
	v_pk_fma_f32 v[36:37], v[208:209], v[182:183], v[36:37] op_sel:[0,1,0]
	v_pk_fma_f32 v[30:31], v[210:211], v[182:183], v[30:31] op_sel:[0,1,0]
	v_pk_fma_f32 v[38:39], v[212:213], v[182:183], v[38:39] op_sel:[0,1,0]
	v_pk_fma_f32 v[28:29], v[214:215], v[182:183], v[28:29] op_sel:[0,1,0]
	global_load_dwordx4 v[180:183], v[34:35], off offset:-8
	v_lshl_add_u64 v[116:117], v[32:33], 0, s[22:23]
	global_load_dwordx4 v[184:187], v[116:117], off
	global_load_dwordx4 v[188:191], v[116:117], off offset:16
	global_load_dwordx4 v[192:195], v[116:117], off offset:512
	global_load_dwordx4 v[196:199], v[116:117], off offset:528
	global_load_dwordx4 v[200:203], v[116:117], off offset:1024
	global_load_dwordx4 v[204:207], v[116:117], off offset:1040
	global_load_dwordx4 v[208:211], v[116:117], off offset:1536
	global_load_dwordx4 v[212:215], v[116:117], off offset:1552
	s_add_u32 s22, s22, 0x800
	s_addc_u32 s23, s23, 0
	v_lshl_add_u64 v[34:35], v[34:35], 0, 16
	s_waitcnt vmcnt(18)
	v_pk_fma_f32 v[36:37], v[84:85], v[80:81], v[36:37] op_sel_hi:[1,0,1]
	v_pk_fma_f32 v[30:31], v[86:87], v[80:81], v[30:31] op_sel_hi:[1,0,1]
	v_pk_fma_f32 v[38:39], v[88:89], v[80:81], v[38:39] op_sel_hi:[1,0,1]
	v_pk_fma_f32 v[28:29], v[90:91], v[80:81], v[28:29] op_sel_hi:[1,0,1]
	v_pk_fma_f32 v[36:37], v[92:93], v[80:81], v[36:37] op_sel:[0,1,0]
	v_pk_fma_f32 v[30:31], v[94:95], v[80:81], v[30:31] op_sel:[0,1,0]
	v_pk_fma_f32 v[38:39], v[96:97], v[80:81], v[38:39] op_sel:[0,1,0]
	v_pk_fma_f32 v[28:29], v[98:99], v[80:81], v[28:29] op_sel:[0,1,0]
	v_pk_fma_f32 v[36:37], v[100:101], v[82:83], v[36:37] op_sel_hi:[1,0,1]
	v_pk_fma_f32 v[30:31], v[102:103], v[82:83], v[30:31] op_sel_hi:[1,0,1]
	v_pk_fma_f32 v[38:39], v[104:105], v[82:83], v[38:39] op_sel_hi:[1,0,1]
	v_pk_fma_f32 v[28:29], v[106:107], v[82:83], v[28:29] op_sel_hi:[1,0,1]
	v_pk_fma_f32 v[36:37], v[108:109], v[82:83], v[36:37] op_sel:[0,1,0]
	v_pk_fma_f32 v[30:31], v[110:111], v[82:83], v[30:31] op_sel:[0,1,0]
	v_pk_fma_f32 v[38:39], v[112:113], v[82:83], v[38:39] op_sel:[0,1,0]
	v_pk_fma_f32 v[28:29], v[114:115], v[82:83], v[28:29] op_sel:[0,1,0]
	global_load_dwordx4 v[80:83], v[34:35], off offset:-8
	v_lshl_add_u64 v[116:117], v[32:33], 0, s[22:23]
	global_load_dwordx4 v[84:87], v[116:117], off
	global_load_dwordx4 v[88:91], v[116:117], off offset:16
	global_load_dwordx4 v[92:95], v[116:117], off offset:512
	global_load_dwordx4 v[96:99], v[116:117], off offset:528
	global_load_dwordx4 v[100:103], v[116:117], off offset:1024
	global_load_dwordx4 v[104:107], v[116:117], off offset:1040
	global_load_dwordx4 v[108:111], v[116:117], off offset:1536
	global_load_dwordx4 v[112:115], v[116:117], off offset:1552
	s_add_u32 s22, s22, 0x800
	s_addc_u32 s23, s23, 0
	v_lshl_add_u64 v[34:35], v[34:35], 0, 16
	s_waitcnt vmcnt(18)
	v_pk_fma_f32 v[36:37], v[148:149], v[144:145], v[36:37] op_sel_hi:[1,0,1]
	v_pk_fma_f32 v[30:31], v[150:151], v[144:145], v[30:31] op_sel_hi:[1,0,1]
	v_pk_fma_f32 v[38:39], v[152:153], v[144:145], v[38:39] op_sel_hi:[1,0,1]
	v_pk_fma_f32 v[28:29], v[154:155], v[144:145], v[28:29] op_sel_hi:[1,0,1]
	v_pk_fma_f32 v[36:37], v[156:157], v[144:145], v[36:37] op_sel:[0,1,0]
	v_pk_fma_f32 v[30:31], v[158:159], v[144:145], v[30:31] op_sel:[0,1,0]
	v_pk_fma_f32 v[38:39], v[160:161], v[144:145], v[38:39] op_sel:[0,1,0]
	v_pk_fma_f32 v[28:29], v[162:163], v[144:145], v[28:29] op_sel:[0,1,0]
	v_pk_fma_f32 v[36:37], v[164:165], v[146:147], v[36:37] op_sel_hi:[1,0,1]
	v_pk_fma_f32 v[30:31], v[166:167], v[146:147], v[30:31] op_sel_hi:[1,0,1]
	v_pk_fma_f32 v[38:39], v[168:169], v[146:147], v[38:39] op_sel_hi:[1,0,1]
	v_pk_fma_f32 v[28:29], v[170:171], v[146:147], v[28:29] op_sel_hi:[1,0,1]
	v_pk_fma_f32 v[36:37], v[172:173], v[146:147], v[36:37] op_sel:[0,1,0]
	v_pk_fma_f32 v[30:31], v[174:175], v[146:147], v[30:31] op_sel:[0,1,0]
	v_pk_fma_f32 v[38:39], v[176:177], v[146:147], v[38:39] op_sel:[0,1,0]
	v_pk_fma_f32 v[28:29], v[178:179], v[146:147], v[28:29] op_sel:[0,1,0]
	global_load_dwordx4 v[144:147], v[34:35], off offset:-8
	v_lshl_add_u64 v[116:117], v[32:33], 0, s[22:23]
	global_load_dwordx4 v[148:151], v[116:117], off
	global_load_dwordx4 v[152:155], v[116:117], off offset:16
	global_load_dwordx4 v[156:159], v[116:117], off offset:512
	global_load_dwordx4 v[160:163], v[116:117], off offset:528
	global_load_dwordx4 v[164:167], v[116:117], off offset:1024
	global_load_dwordx4 v[168:171], v[116:117], off offset:1040
	global_load_dwordx4 v[172:175], v[116:117], off offset:1536
	global_load_dwordx4 v[176:179], v[116:117], off offset:1552
	s_add_u32 s22, s22, 0x800
	s_addc_u32 s23, s23, 0
	v_lshl_add_u64 v[34:35], v[34:35], 0, 16
	s_waitcnt vmcnt(18)
; __device__ __forceinline__ void wcomb_item(const float* w_in, const float* wg, const float* ngain, bf16_t* WinT, int item, int lane) {
;     ...
; #pragma unroll 4
;     for (int cin = 0; cin < 128; ++cin) { const float av = ap[cin]; const f32x4 b0 = *(const f32x4*)(bp + (size_t)cin * 128), b1 = *(const f32x4*)(bp + (size_t)cin * 128 + 4); c0 += b0 * av; c1 += b1 * av; }
	v_pk_fma_f32 v[36:37], v[184:185], v[180:181], v[36:37] op_sel_hi:[1,0,1]
	v_pk_fma_f32 v[30:31], v[186:187], v[180:181], v[30:31] op_sel_hi:[1,0,1]
	v_pk_fma_f32 v[38:39], v[188:189], v[180:181], v[38:39] op_sel_hi:[1,0,1]
	v_pk_fma_f32 v[28:29], v[190:191], v[180:181], v[28:29] op_sel_hi:[1,0,1]
	v_pk_fma_f32 v[36:37], v[192:193], v[180:181], v[36:37] op_sel:[0,1,0]
	v_pk_fma_f32 v[30:31], v[194:195], v[180:181], v[30:31] op_sel:[0,1,0]
	v_pk_fma_f32 v[38:39], v[196:197], v[180:181], v[38:39] op_sel:[0,1,0]
	v_pk_fma_f32 v[28:29], v[198:199], v[180:181], v[28:29] op_sel:[0,1,0]
	v_pk_fma_f32 v[36:37], v[200:201], v[182:183], v[36:37] op_sel_hi:[1,0,1]
	v_pk_fma_f32 v[30:31], v[202:203], v[182:183], v[30:31] op_sel_hi:[1,0,1]
	v_pk_fma_f32 v[38:39], v[204:205], v[182:183], v[38:39] op_sel_hi:[1,0,1]
	v_pk_fma_f32 v[28:29], v[206:207], v[182:183], v[28:29] op_sel_hi:[1,0,1]
	v_pk_fma_f32 v[36:37], v[208:209], v[182:183], v[36:37] op_sel:[0,1,0]
	v_pk_fma_f32 v[30:31], v[210:211], v[182:183], v[30:31] op_sel:[0,1,0]
	v_pk_fma_f32 v[38:39], v[212:213], v[182:183], v[38:39] op_sel:[0,1,0]
	v_pk_fma_f32 v[28:29], v[214:215], v[182:183], v[28:29] op_sel:[0,1,0]
	global_load_dwordx4 v[180:183], v[34:35], off offset:-8
	v_lshl_add_u64 v[116:117], v[32:33], 0, s[22:23]
	global_load_dwordx4 v[184:187], v[116:117], off
	global_load_dwordx4 v[188:191], v[116:117], off offset:16
	global_load_dwordx4 v[192:195], v[116:117], off offset:512
	global_load_dwordx4 v[196:199], v[116:117], off offset:528
	global_load_dwordx4 v[200:203], v[116:117], off offset:1024
	global_load_dwordx4 v[204:207], v[116:117], off offset:1040
	global_load_dwordx4 v[208:211], v[116:117], off offset:1536
	global_load_dwordx4 v[212:215], v[116:117], off offset:1552
	s_add_u32 s22, s22, 0x800
	s_addc_u32 s23, s23, 0
	v_lshl_add_u64 v[34:35], v[34:35], 0, 16
	s_waitcnt vmcnt(18)
	v_pk_fma_f32 v[36:37], v[84:85], v[80:81], v[36:37] op_sel_hi:[1,0,1]
	v_pk_fma_f32 v[30:31], v[86:87], v[80:81], v[30:31] op_sel_hi:[1,0,1]
	v_pk_fma_f32 v[38:39], v[88:89], v[80:81], v[38:39] op_sel_hi:[1,0,1]
	v_pk_fma_f32 v[28:29], v[90:91], v[80:81], v[28:29] op_sel_hi:[1,0,1]
	v_pk_fma_f32 v[36:37], v[92:93], v[80:81], v[36:37] op_sel:[0,1,0]
	v_pk_fma_f32 v[30:31], v[94:95], v[80:81], v[30:31] op_sel:[0,1,0]
	v_pk_fma_f32 v[38:39], v[96:97], v[80:81], v[38:39] op_sel:[0,1,0]
	v_pk_fma_f32 v[28:29], v[98:99], v[80:81], v[28:29] op_sel:[0,1,0]
	v_pk_fma_f32 v[36:37], v[100:101], v[82:83], v[36:37] op_sel_hi:[1,0,1]
	v_pk_fma_f32 v[30:31], v[102:103], v[82:83], v[30:31] op_sel_hi:[1,0,1]
	v_pk_fma_f32 v[38:39], v[104:105], v[82:83], v[38:39] op_sel_hi:[1,0,1]
	v_pk_fma_f32 v[28:29], v[106:107], v[82:83], v[28:29] op_sel_hi:[1,0,1]
	v_pk_fma_f32 v[36:37], v[108:109], v[82:83], v[36:37] op_sel:[0,1,0]
	v_pk_fma_f32 v[30:31], v[110:111], v[82:83], v[30:31] op_sel:[0,1,0]
	v_pk_fma_f32 v[38:39], v[112:113], v[82:83], v[38:39] op_sel:[0,1,0]
	v_pk_fma_f32 v[28:29], v[114:115], v[82:83], v[28:29] op_sel:[0,1,0]
	global_load_dwordx4 v[80:83], v[34:35], off offset:-8
	v_lshl_add_u64 v[116:117], v[32:33], 0, s[22:23]
	global_load_dwordx4 v[84:87], v[116:117], off
	global_load_dwordx4 v[88:91], v[116:117], off offset:16
	global_load_dwordx4 v[92:95], v[116:117], off offset:512
	global_load_dwordx4 v[96:99], v[116:117], off offset:528
	global_load_dwordx4 v[100:103], v[116:117], off offset:1024
	global_load_dwordx4 v[104:107], v[116:117], off offset:1040
	global_load_dwordx4 v[108:111], v[116:117], off offset:1536
	global_load_dwordx4 v[112:115], v[116:117], off offset:1552
	s_add_u32 s22, s22, 0x800
	s_addc_u32 s23, s23, 0
	v_lshl_add_u64 v[34:35], v[34:35], 0, 16
	s_waitcnt vmcnt(18)
	v_pk_fma_f32 v[36:37], v[148:149], v[144:145], v[36:37] op_sel_hi:[1,0,1]
	v_pk_fma_f32 v[30:31], v[150:151], v[144:145], v[30:31] op_sel_hi:[1,0,1]
	v_pk_fma_f32 v[38:39], v[152:153], v[144:145], v[38:39] op_sel_hi:[1,0,1]
	v_pk_fma_f32 v[28:29], v[154:155], v[144:145], v[28:29] op_sel_hi:[1,0,1]
	v_pk_fma_f32 v[36:37], v[156:157], v[144:145], v[36:37] op_sel:[0,1,0]
	v_pk_fma_f32 v[30:31], v[158:159], v[144:145], v[30:31] op_sel:[0,1,0]
	v_pk_fma_f32 v[38:39], v[160:161], v[144:145], v[38:39] op_sel:[0,1,0]
	v_pk_fma_f32 v[28:29], v[162:163], v[144:145], v[28:29] op_sel:[0,1,0]
	v_pk_fma_f32 v[36:37], v[164:165], v[146:147], v[36:37] op_sel_hi:[1,0,1]
	v_pk_fma_f32 v[30:31], v[166:167], v[146:147], v[30:31] op_sel_hi:[1,0,1]
	v_pk_fma_f32 v[38:39], v[168:169], v[146:147], v[38:39] op_sel_hi:[1,0,1]
	v_pk_fma_f32 v[28:29], v[170:171], v[146:147], v[28:29] op_sel_hi:[1,0,1]
	v_pk_fma_f32 v[36:37], v[172:173], v[146:147], v[36:37] op_sel:[0,1,0]
	v_pk_fma_f32 v[30:31], v[174:175], v[146:147], v[30:31] op_sel:[0,1,0]
	v_pk_fma_f32 v[38:39], v[176:177], v[146:147], v[38:39] op_sel:[0,1,0]
	v_pk_fma_f32 v[28:29], v[178:179], v[146:147], v[28:29] op_sel:[0,1,0]
	global_load_dwordx4 v[144:147], v[34:35], off offset:-8
	v_lshl_add_u64 v[116:117], v[32:33], 0, s[22:23]
	global_load_dwordx4 v[148:151], v[116:117], off
	global_load_dwordx4 v[152:155], v[116:117], off offset:16
	global_load_dwordx4 v[156:159], v[116:117], off offset:512
	global_load_dwordx4 v[160:163], v[116:117], off offset:528
	global_load_dwordx4 v[164:167], v[116:117], off offset:1024
	global_load_dwordx4 v[168:171], v[116:117], off offset:1040
	global_load_dwordx4 v[172:175], v[116:117], off offset:1536
	global_load_dwordx4 v[176:179], v[116:117], off offset:1552
	s_add_u32 s22, s22, 0x800
	s_addc_u32 s23, s23, 0
	v_lshl_add_u64 v[34:35], v[34:35], 0, 16
	s_waitcnt vmcnt(18)
; __device__ __forceinline__ void wcomb_item(const float* w_in, const float* wg, const float* ngain, bf16_t* WinT, int item, int lane) {
;     ...
; #pragma unroll 4
;     for (int cin = 0; cin < 128; ++cin) { const float av = ap[cin]; const f32x4 b0 = *(const f32x4*)(bp + (size_t)cin * 128), b1 = *(const f32x4*)(bp + (size_t)cin * 128 + 4); c0 += b0 * av; c1 += b1 * av; }
	v_pk_fma_f32 v[36:37], v[184:185], v[180:181], v[36:37] op_sel_hi:[1,0,1]
	v_pk_fma_f32 v[30:31], v[186:187], v[180:181], v[30:31] op_sel_hi:[1,0,1]
	v_pk_fma_f32 v[38:39], v[188:189], v[180:181], v[38:39] op_sel_hi:[1,0,1]
	v_pk_fma_f32 v[28:29], v[190:191], v[180:181], v[28:29] op_sel_hi:[1,0,1]
	v_pk_fma_f32 v[36:37], v[192:193], v[180:181], v[36:37] op_sel:[0,1,0]
	v_pk_fma_f32 v[30:31], v[194:195], v[180:181], v[30:31] op_sel:[0,1,0]
	v_pk_fma_f32 v[38:39], v[196:197], v[180:181], v[38:39] op_sel:[0,1,0]
	v_pk_fma_f32 v[28:29], v[198:199], v[180:181], v[28:29] op_sel:[0,1,0]
	v_pk_fma_f32 v[36:37], v[200:201], v[182:183], v[36:37] op_sel_hi:[1,0,1]
	v_pk_fma_f32 v[30:31], v[202:203], v[182:183], v[30:31] op_sel_hi:[1,0,1]
	v_pk_fma_f32 v[38:39], v[204:205], v[182:183], v[38:39] op_sel_hi:[1,0,1]
	v_pk_fma_f32 v[28:29], v[206:207], v[182:183], v[28:29] op_sel_hi:[1,0,1]
	v_pk_fma_f32 v[36:37], v[208:209], v[182:183], v[36:37] op_sel:[0,1,0]
	v_pk_fma_f32 v[30:31], v[210:211], v[182:183], v[30:31] op_sel:[0,1,0]
	v_pk_fma_f32 v[38:39], v[212:213], v[182:183], v[38:39] op_sel:[0,1,0]
	v_pk_fma_f32 v[28:29], v[214:215], v[182:183], v[28:29] op_sel:[0,1,0]
	global_load_dwordx4 v[180:183], v[34:35], off offset:-8
	v_lshl_add_u64 v[116:117], v[32:33], 0, s[22:23]
	global_load_dwordx4 v[184:187], v[116:117], off
	global_load_dwordx4 v[188:191], v[116:117], off offset:16
	global_load_dwordx4 v[192:195], v[116:117], off offset:512
	global_load_dwordx4 v[196:199], v[116:117], off offset:528
	global_load_dwordx4 v[200:203], v[116:117], off offset:1024
	global_load_dwordx4 v[204:207], v[116:117], off offset:1040
	global_load_dwordx4 v[208:211], v[116:117], off offset:1536
	global_load_dwordx4 v[212:215], v[116:117], off offset:1552
	s_add_u32 s22, s22, 0x800
	s_addc_u32 s23, s23, 0
	v_lshl_add_u64 v[34:35], v[34:35], 0, 16
	s_waitcnt vmcnt(18)
	v_pk_fma_f32 v[36:37], v[84:85], v[80:81], v[36:37] op_sel_hi:[1,0,1]
	v_pk_fma_f32 v[30:31], v[86:87], v[80:81], v[30:31] op_sel_hi:[1,0,1]
	v_pk_fma_f32 v[38:39], v[88:89], v[80:81], v[38:39] op_sel_hi:[1,0,1]
	v_pk_fma_f32 v[28:29], v[90:91], v[80:81], v[28:29] op_sel_hi:[1,0,1]
	v_pk_fma_f32 v[36:37], v[92:93], v[80:81], v[36:37] op_sel:[0,1,0]
	v_pk_fma_f32 v[30:31], v[94:95], v[80:81], v[30:31] op_sel:[0,1,0]
	v_pk_fma_f32 v[38:39], v[96:97], v[80:81], v[38:39] op_sel:[0,1,0]
	v_pk_fma_f32 v[28:29], v[98:99], v[80:81], v[28:29] op_sel:[0,1,0]
	v_pk_fma_f32 v[36:37], v[100:101], v[82:83], v[36:37] op_sel_hi:[1,0,1]
	v_pk_fma_f32 v[30:31], v[102:103], v[82:83], v[30:31] op_sel_hi:[1,0,1]
	v_pk_fma_f32 v[38:39], v[104:105], v[82:83], v[38:39] op_sel_hi:[1,0,1]
	v_pk_fma_f32 v[28:29], v[106:107], v[82:83], v[28:29] op_sel_hi:[1,0,1]
	v_pk_fma_f32 v[36:37], v[108:109], v[82:83], v[36:37] op_sel:[0,1,0]
	v_pk_fma_f32 v[30:31], v[110:111], v[82:83], v[30:31] op_sel:[0,1,0]
	v_pk_fma_f32 v[38:39], v[112:113], v[82:83], v[38:39] op_sel:[0,1,0]
	v_pk_fma_f32 v[28:29], v[114:115], v[82:83], v[28:29] op_sel:[0,1,0]
	global_load_dwordx4 v[80:83], v[34:35], off offset:-8
	v_lshl_add_u64 v[116:117], v[32:33], 0, s[22:23]
	global_load_dwordx4 v[84:87], v[116:117], off
	global_load_dwordx4 v[88:91], v[116:117], off offset:16
	global_load_dwordx4 v[92:95], v[116:117], off offset:512
	global_load_dwordx4 v[96:99], v[116:117], off offset:528
	global_load_dwordx4 v[100:103], v[116:117], off offset:1024
	global_load_dwordx4 v[104:107], v[116:117], off offset:1040
	global_load_dwordx4 v[108:111], v[116:117], off offset:1536
	global_load_dwordx4 v[112:115], v[116:117], off offset:1552
	s_add_u32 s22, s22, 0x800
	s_addc_u32 s23, s23, 0
	v_lshl_add_u64 v[34:35], v[34:35], 0, 16
	s_waitcnt vmcnt(18)
	v_pk_fma_f32 v[36:37], v[148:149], v[144:145], v[36:37] op_sel_hi:[1,0,1]
	v_pk_fma_f32 v[30:31], v[150:151], v[144:145], v[30:31] op_sel_hi:[1,0,1]
	v_pk_fma_f32 v[38:39], v[152:153], v[144:145], v[38:39] op_sel_hi:[1,0,1]
	v_pk_fma_f32 v[28:29], v[154:155], v[144:145], v[28:29] op_sel_hi:[1,0,1]
	v_pk_fma_f32 v[36:37], v[156:157], v[144:145], v[36:37] op_sel:[0,1,0]
	v_pk_fma_f32 v[30:31], v[158:159], v[144:145], v[30:31] op_sel:[0,1,0]
	v_pk_fma_f32 v[38:39], v[160:161], v[144:145], v[38:39] op_sel:[0,1,0]
	v_pk_fma_f32 v[28:29], v[162:163], v[144:145], v[28:29] op_sel:[0,1,0]
	v_pk_fma_f32 v[36:37], v[164:165], v[146:147], v[36:37] op_sel_hi:[1,0,1]
	v_pk_fma_f32 v[30:31], v[166:167], v[146:147], v[30:31] op_sel_hi:[1,0,1]
	v_pk_fma_f32 v[38:39], v[168:169], v[146:147], v[38:39] op_sel_hi:[1,0,1]
	v_pk_fma_f32 v[28:29], v[170:171], v[146:147], v[28:29] op_sel_hi:[1,0,1]
	v_pk_fma_f32 v[36:37], v[172:173], v[146:147], v[36:37] op_sel:[0,1,0]
	v_pk_fma_f32 v[30:31], v[174:175], v[146:147], v[30:31] op_sel:[0,1,0]
	v_pk_fma_f32 v[38:39], v[176:177], v[146:147], v[38:39] op_sel:[0,1,0]
	v_pk_fma_f32 v[28:29], v[178:179], v[146:147], v[28:29] op_sel:[0,1,0]
	global_load_dwordx4 v[144:147], v[34:35], off offset:-8
	v_lshl_add_u64 v[116:117], v[32:33], 0, s[22:23]
	global_load_dwordx4 v[148:151], v[116:117], off
	global_load_dwordx4 v[152:155], v[116:117], off offset:16
	global_load_dwordx4 v[156:159], v[116:117], off offset:512
	global_load_dwordx4 v[160:163], v[116:117], off offset:528
	global_load_dwordx4 v[164:167], v[116:117], off offset:1024
	global_load_dwordx4 v[168:171], v[116:117], off offset:1040
	global_load_dwordx4 v[172:175], v[116:117], off offset:1536
	global_load_dwordx4 v[176:179], v[116:117], off offset:1552
	s_add_u32 s22, s22, 0x800
	s_addc_u32 s23, s23, 0
	v_lshl_add_u64 v[34:35], v[34:35], 0, 16
	s_waitcnt vmcnt(18)
; __device__ __forceinline__ void wcomb_item(const float* w_in, const float* wg, const float* ngain, bf16_t* WinT, int item, int lane) {
;     ...
; #pragma unroll 4
;     for (int cin = 0; cin < 128; ++cin) { const float av = ap[cin]; const f32x4 b0 = *(const f32x4*)(bp + (size_t)cin * 128), b1 = *(const f32x4*)(bp + (size_t)cin * 128 + 4); c0 += b0 * av; c1 += b1 * av; }
	v_pk_fma_f32 v[36:37], v[184:185], v[180:181], v[36:37] op_sel_hi:[1,0,1]
	v_pk_fma_f32 v[30:31], v[186:187], v[180:181], v[30:31] op_sel_hi:[1,0,1]
	v_pk_fma_f32 v[38:39], v[188:189], v[180:181], v[38:39] op_sel_hi:[1,0,1]
	v_pk_fma_f32 v[28:29], v[190:191], v[180:181], v[28:29] op_sel_hi:[1,0,1]
	v_pk_fma_f32 v[36:37], v[192:193], v[180:181], v[36:37] op_sel:[0,1,0]
	v_pk_fma_f32 v[30:31], v[194:195], v[180:181], v[30:31] op_sel:[0,1,0]
	v_pk_fma_f32 v[38:39], v[196:197], v[180:181], v[38:39] op_sel:[0,1,0]
	v_pk_fma_f32 v[28:29], v[198:199], v[180:181], v[28:29] op_sel:[0,1,0]
	v_pk_fma_f32 v[36:37], v[200:201], v[182:183], v[36:37] op_sel_hi:[1,0,1]
	v_pk_fma_f32 v[30:31], v[202:203], v[182:183], v[30:31] op_sel_hi:[1,0,1]
	v_pk_fma_f32 v[38:39], v[204:205], v[182:183], v[38:39] op_sel_hi:[1,0,1]
	v_pk_fma_f32 v[28:29], v[206:207], v[182:183], v[28:29] op_sel_hi:[1,0,1]
	v_pk_fma_f32 v[36:37], v[208:209], v[182:183], v[36:37] op_sel:[0,1,0]
	v_pk_fma_f32 v[30:31], v[210:211], v[182:183], v[30:31] op_sel:[0,1,0]
	v_pk_fma_f32 v[38:39], v[212:213], v[182:183], v[38:39] op_sel:[0,1,0]
	v_pk_fma_f32 v[28:29], v[214:215], v[182:183], v[28:29] op_sel:[0,1,0]
	global_load_dwordx4 v[180:183], v[34:35], off offset:-8
	v_lshl_add_u64 v[116:117], v[32:33], 0, s[22:23]
	global_load_dwordx4 v[184:187], v[116:117], off
	global_load_dwordx4 v[188:191], v[116:117], off offset:16
	global_load_dwordx4 v[192:195], v[116:117], off offset:512
	global_load_dwordx4 v[196:199], v[116:117], off offset:528
	global_load_dwordx4 v[200:203], v[116:117], off offset:1024
	global_load_dwordx4 v[204:207], v[116:117], off offset:1040
	global_load_dwordx4 v[208:211], v[116:117], off offset:1536
	global_load_dwordx4 v[212:215], v[116:117], off offset:1552
	s_add_u32 s22, s22, 0x800
	s_addc_u32 s23, s23, 0
	v_lshl_add_u64 v[34:35], v[34:35], 0, 16
	s_waitcnt vmcnt(18)
	v_pk_fma_f32 v[36:37], v[84:85], v[80:81], v[36:37] op_sel_hi:[1,0,1]
	v_pk_fma_f32 v[30:31], v[86:87], v[80:81], v[30:31] op_sel_hi:[1,0,1]
	v_pk_fma_f32 v[38:39], v[88:89], v[80:81], v[38:39] op_sel_hi:[1,0,1]
	v_pk_fma_f32 v[28:29], v[90:91], v[80:81], v[28:29] op_sel_hi:[1,0,1]
	v_pk_fma_f32 v[36:37], v[92:93], v[80:81], v[36:37] op_sel:[0,1,0]
	v_pk_fma_f32 v[30:31], v[94:95], v[80:81], v[30:31] op_sel:[0,1,0]
	v_pk_fma_f32 v[38:39], v[96:97], v[80:81], v[38:39] op_sel:[0,1,0]
	v_pk_fma_f32 v[28:29], v[98:99], v[80:81], v[28:29] op_sel:[0,1,0]
	v_pk_fma_f32 v[36:37], v[100:101], v[82:83], v[36:37] op_sel_hi:[1,0,1]
	v_pk_fma_f32 v[30:31], v[102:103], v[82:83], v[30:31] op_sel_hi:[1,0,1]
	v_pk_fma_f32 v[38:39], v[104:105], v[82:83], v[38:39] op_sel_hi:[1,0,1]
	v_pk_fma_f32 v[28:29], v[106:107], v[82:83], v[28:29] op_sel_hi:[1,0,1]
	v_pk_fma_f32 v[36:37], v[108:109], v[82:83], v[36:37] op_sel:[0,1,0]
	v_pk_fma_f32 v[30:31], v[110:111], v[82:83], v[30:31] op_sel:[0,1,0]
	v_pk_fma_f32 v[38:39], v[112:113], v[82:83], v[38:39] op_sel:[0,1,0]
	v_pk_fma_f32 v[28:29], v[114:115], v[82:83], v[28:29] op_sel:[0,1,0]
	global_load_dwordx4 v[80:83], v[34:35], off offset:-8
	v_lshl_add_u64 v[116:117], v[32:33], 0, s[22:23]
	global_load_dwordx4 v[84:87], v[116:117], off
	global_load_dwordx4 v[88:91], v[116:117], off offset:16
	global_load_dwordx4 v[92:95], v[116:117], off offset:512
	global_load_dwordx4 v[96:99], v[116:117], off offset:528
	global_load_dwordx4 v[100:103], v[116:117], off offset:1024
	global_load_dwordx4 v[104:107], v[116:117], off offset:1040
	global_load_dwordx4 v[108:111], v[116:117], off offset:1536
	global_load_dwordx4 v[112:115], v[116:117], off offset:1552
	s_add_u32 s22, s22, 0x800
	s_addc_u32 s23, s23, 0
	v_lshl_add_u64 v[34:35], v[34:35], 0, 16
	s_waitcnt vmcnt(18)
	v_pk_fma_f32 v[36:37], v[148:149], v[144:145], v[36:37] op_sel_hi:[1,0,1]
	v_pk_fma_f32 v[30:31], v[150:151], v[144:145], v[30:31] op_sel_hi:[1,0,1]
	v_pk_fma_f32 v[38:39], v[152:153], v[144:145], v[38:39] op_sel_hi:[1,0,1]
	v_pk_fma_f32 v[28:29], v[154:155], v[144:145], v[28:29] op_sel_hi:[1,0,1]
	v_pk_fma_f32 v[36:37], v[156:157], v[144:145], v[36:37] op_sel:[0,1,0]
	v_pk_fma_f32 v[30:31], v[158:159], v[144:145], v[30:31] op_sel:[0,1,0]
	v_pk_fma_f32 v[38:39], v[160:161], v[144:145], v[38:39] op_sel:[0,1,0]
	v_pk_fma_f32 v[28:29], v[162:163], v[144:145], v[28:29] op_sel:[0,1,0]
	v_pk_fma_f32 v[36:37], v[164:165], v[146:147], v[36:37] op_sel_hi:[1,0,1]
	v_pk_fma_f32 v[30:31], v[166:167], v[146:147], v[30:31] op_sel_hi:[1,0,1]
	v_pk_fma_f32 v[38:39], v[168:169], v[146:147], v[38:39] op_sel_hi:[1,0,1]
	v_pk_fma_f32 v[28:29], v[170:171], v[146:147], v[28:29] op_sel_hi:[1,0,1]
	v_pk_fma_f32 v[36:37], v[172:173], v[146:147], v[36:37] op_sel:[0,1,0]
	v_pk_fma_f32 v[30:31], v[174:175], v[146:147], v[30:31] op_sel:[0,1,0]
	v_pk_fma_f32 v[38:39], v[176:177], v[146:147], v[38:39] op_sel:[0,1,0]
	v_pk_fma_f32 v[28:29], v[178:179], v[146:147], v[28:29] op_sel:[0,1,0]
	global_load_dwordx4 v[144:147], v[34:35], off offset:-8
	v_lshl_add_u64 v[116:117], v[32:33], 0, s[22:23]
	global_load_dwordx4 v[148:151], v[116:117], off
	global_load_dwordx4 v[152:155], v[116:117], off offset:16
	global_load_dwordx4 v[156:159], v[116:117], off offset:512
	global_load_dwordx4 v[160:163], v[116:117], off offset:528
	global_load_dwordx4 v[164:167], v[116:117], off offset:1024
	global_load_dwordx4 v[168:171], v[116:117], off offset:1040
	global_load_dwordx4 v[172:175], v[116:117], off offset:1536
	global_load_dwordx4 v[176:179], v[116:117], off offset:1552
	s_add_u32 s22, s22, 0x800
	s_addc_u32 s23, s23, 0
	v_lshl_add_u64 v[34:35], v[34:35], 0, 16
	s_waitcnt vmcnt(18)
; __device__ __forceinline__ void wcomb_item(const float* w_in, const float* wg, const float* ngain, bf16_t* WinT, int item, int lane) {
;     ...
; #pragma unroll 4
;     for (int cin = 0; cin < 128; ++cin) { const float av = ap[cin]; const f32x4 b0 = *(const f32x4*)(bp + (size_t)cin * 128), b1 = *(const f32x4*)(bp + (size_t)cin * 128 + 4); c0 += b0 * av; c1 += b1 * av; }
	v_pk_fma_f32 v[36:37], v[184:185], v[180:181], v[36:37] op_sel_hi:[1,0,1]
	v_pk_fma_f32 v[30:31], v[186:187], v[180:181], v[30:31] op_sel_hi:[1,0,1]
	v_pk_fma_f32 v[38:39], v[188:189], v[180:181], v[38:39] op_sel_hi:[1,0,1]
	v_pk_fma_f32 v[28:29], v[190:191], v[180:181], v[28:29] op_sel_hi:[1,0,1]
	v_pk_fma_f32 v[36:37], v[192:193], v[180:181], v[36:37] op_sel:[0,1,0]
	v_pk_fma_f32 v[30:31], v[194:195], v[180:181], v[30:31] op_sel:[0,1,0]
	v_pk_fma_f32 v[38:39], v[196:197], v[180:181], v[38:39] op_sel:[0,1,0]
	v_pk_fma_f32 v[28:29], v[198:199], v[180:181], v[28:29] op_sel:[0,1,0]
	v_pk_fma_f32 v[36:37], v[200:201], v[182:183], v[36:37] op_sel_hi:[1,0,1]
	v_pk_fma_f32 v[30:31], v[202:203], v[182:183], v[30:31] op_sel_hi:[1,0,1]
	v_pk_fma_f32 v[38:39], v[204:205], v[182:183], v[38:39] op_sel_hi:[1,0,1]
	v_pk_fma_f32 v[28:29], v[206:207], v[182:183], v[28:29] op_sel_hi:[1,0,1]
	v_pk_fma_f32 v[36:37], v[208:209], v[182:183], v[36:37] op_sel:[0,1,0]
	v_pk_fma_f32 v[30:31], v[210:211], v[182:183], v[30:31] op_sel:[0,1,0]
	v_pk_fma_f32 v[38:39], v[212:213], v[182:183], v[38:39] op_sel:[0,1,0]
	v_pk_fma_f32 v[28:29], v[214:215], v[182:183], v[28:29] op_sel:[0,1,0]
	global_load_dwordx4 v[180:183], v[34:35], off offset:-8
	v_lshl_add_u64 v[116:117], v[32:33], 0, s[22:23]
	global_load_dwordx4 v[184:187], v[116:117], off
	global_load_dwordx4 v[188:191], v[116:117], off offset:16
	global_load_dwordx4 v[192:195], v[116:117], off offset:512
	global_load_dwordx4 v[196:199], v[116:117], off offset:528
	global_load_dwordx4 v[200:203], v[116:117], off offset:1024
	global_load_dwordx4 v[204:207], v[116:117], off offset:1040
	global_load_dwordx4 v[208:211], v[116:117], off offset:1536
	global_load_dwordx4 v[212:215], v[116:117], off offset:1552
	s_add_u32 s22, s22, 0x800
	s_addc_u32 s23, s23, 0
	v_lshl_add_u64 v[34:35], v[34:35], 0, 16
	s_waitcnt vmcnt(18)
	v_pk_fma_f32 v[36:37], v[84:85], v[80:81], v[36:37] op_sel_hi:[1,0,1]
	v_pk_fma_f32 v[30:31], v[86:87], v[80:81], v[30:31] op_sel_hi:[1,0,1]
	v_pk_fma_f32 v[38:39], v[88:89], v[80:81], v[38:39] op_sel_hi:[1,0,1]
	v_pk_fma_f32 v[28:29], v[90:91], v[80:81], v[28:29] op_sel_hi:[1,0,1]
	v_pk_fma_f32 v[36:37], v[92:93], v[80:81], v[36:37] op_sel:[0,1,0]
	v_pk_fma_f32 v[30:31], v[94:95], v[80:81], v[30:31] op_sel:[0,1,0]
	v_pk_fma_f32 v[38:39], v[96:97], v[80:81], v[38:39] op_sel:[0,1,0]
	v_pk_fma_f32 v[28:29], v[98:99], v[80:81], v[28:29] op_sel:[0,1,0]
	v_pk_fma_f32 v[36:37], v[100:101], v[82:83], v[36:37] op_sel_hi:[1,0,1]
	v_pk_fma_f32 v[30:31], v[102:103], v[82:83], v[30:31] op_sel_hi:[1,0,1]
	v_pk_fma_f32 v[38:39], v[104:105], v[82:83], v[38:39] op_sel_hi:[1,0,1]
	v_pk_fma_f32 v[28:29], v[106:107], v[82:83], v[28:29] op_sel_hi:[1,0,1]
	v_pk_fma_f32 v[36:37], v[108:109], v[82:83], v[36:37] op_sel:[0,1,0]
	v_pk_fma_f32 v[30:31], v[110:111], v[82:83], v[30:31] op_sel:[0,1,0]
	v_pk_fma_f32 v[38:39], v[112:113], v[82:83], v[38:39] op_sel:[0,1,0]
	v_pk_fma_f32 v[28:29], v[114:115], v[82:83], v[28:29] op_sel:[0,1,0]
	global_load_dwordx4 v[80:83], v[34:35], off offset:-8
	v_lshl_add_u64 v[116:117], v[32:33], 0, s[22:23]
	global_load_dwordx4 v[84:87], v[116:117], off
	global_load_dwordx4 v[88:91], v[116:117], off offset:16
	global_load_dwordx4 v[92:95], v[116:117], off offset:512
	global_load_dwordx4 v[96:99], v[116:117], off offset:528
	global_load_dwordx4 v[100:103], v[116:117], off offset:1024
	global_load_dwordx4 v[104:107], v[116:117], off offset:1040
	global_load_dwordx4 v[108:111], v[116:117], off offset:1536
	global_load_dwordx4 v[112:115], v[116:117], off offset:1552
	s_add_u32 s22, s22, 0x800
	s_addc_u32 s23, s23, 0
	v_lshl_add_u64 v[34:35], v[34:35], 0, 16
	s_waitcnt vmcnt(18)
	v_pk_fma_f32 v[36:37], v[148:149], v[144:145], v[36:37] op_sel_hi:[1,0,1]
	v_pk_fma_f32 v[30:31], v[150:151], v[144:145], v[30:31] op_sel_hi:[1,0,1]
	v_pk_fma_f32 v[38:39], v[152:153], v[144:145], v[38:39] op_sel_hi:[1,0,1]
	v_pk_fma_f32 v[28:29], v[154:155], v[144:145], v[28:29] op_sel_hi:[1,0,1]
	v_pk_fma_f32 v[36:37], v[156:157], v[144:145], v[36:37] op_sel:[0,1,0]
	v_pk_fma_f32 v[30:31], v[158:159], v[144:145], v[30:31] op_sel:[0,1,0]
	v_pk_fma_f32 v[38:39], v[160:161], v[144:145], v[38:39] op_sel:[0,1,0]
	v_pk_fma_f32 v[28:29], v[162:163], v[144:145], v[28:29] op_sel:[0,1,0]
	v_pk_fma_f32 v[36:37], v[164:165], v[146:147], v[36:37] op_sel_hi:[1,0,1]
	v_pk_fma_f32 v[30:31], v[166:167], v[146:147], v[30:31] op_sel_hi:[1,0,1]
	v_pk_fma_f32 v[38:39], v[168:169], v[146:147], v[38:39] op_sel_hi:[1,0,1]
	v_pk_fma_f32 v[28:29], v[170:171], v[146:147], v[28:29] op_sel_hi:[1,0,1]
	v_pk_fma_f32 v[36:37], v[172:173], v[146:147], v[36:37] op_sel:[0,1,0]
	v_pk_fma_f32 v[30:31], v[174:175], v[146:147], v[30:31] op_sel:[0,1,0]
	v_pk_fma_f32 v[38:39], v[176:177], v[146:147], v[38:39] op_sel:[0,1,0]
	v_pk_fma_f32 v[28:29], v[178:179], v[146:147], v[28:29] op_sel:[0,1,0]
	global_load_dwordx4 v[144:147], v[34:35], off offset:-8
	v_lshl_add_u64 v[116:117], v[32:33], 0, s[22:23]
	global_load_dwordx4 v[148:151], v[116:117], off
	global_load_dwordx4 v[152:155], v[116:117], off offset:16
	global_load_dwordx4 v[156:159], v[116:117], off offset:512
	global_load_dwordx4 v[160:163], v[116:117], off offset:528
	global_load_dwordx4 v[164:167], v[116:117], off offset:1024
	global_load_dwordx4 v[168:171], v[116:117], off offset:1040
	global_load_dwordx4 v[172:175], v[116:117], off offset:1536
	global_load_dwordx4 v[176:179], v[116:117], off offset:1552
	s_add_u32 s22, s22, 0x800
	s_addc_u32 s23, s23, 0
	v_lshl_add_u64 v[34:35], v[34:35], 0, 16
	s_waitcnt vmcnt(18)
; __device__ __forceinline__ void wcomb_item(const float* w_in, const float* wg, const float* ngain, bf16_t* WinT, int item, int lane) {
;     ...
; #pragma unroll 4
;     for (int cin = 0; cin < 128; ++cin) { const float av = ap[cin]; const f32x4 b0 = *(const f32x4*)(bp + (size_t)cin * 128), b1 = *(const f32x4*)(bp + (size_t)cin * 128 + 4); c0 += b0 * av; c1 += b1 * av; }
	v_pk_fma_f32 v[36:37], v[184:185], v[180:181], v[36:37] op_sel_hi:[1,0,1]
	v_pk_fma_f32 v[30:31], v[186:187], v[180:181], v[30:31] op_sel_hi:[1,0,1]
	v_pk_fma_f32 v[38:39], v[188:189], v[180:181], v[38:39] op_sel_hi:[1,0,1]
	v_pk_fma_f32 v[28:29], v[190:191], v[180:181], v[28:29] op_sel_hi:[1,0,1]
	v_pk_fma_f32 v[36:37], v[192:193], v[180:181], v[36:37] op_sel:[0,1,0]
	v_pk_fma_f32 v[30:31], v[194:195], v[180:181], v[30:31] op_sel:[0,1,0]
	v_pk_fma_f32 v[38:39], v[196:197], v[180:181], v[38:39] op_sel:[0,1,0]
	v_pk_fma_f32 v[28:29], v[198:199], v[180:181], v[28:29] op_sel:[0,1,0]
	v_pk_fma_f32 v[36:37], v[200:201], v[182:183], v[36:37] op_sel_hi:[1,0,1]
	v_pk_fma_f32 v[30:31], v[202:203], v[182:183], v[30:31] op_sel_hi:[1,0,1]
	v_pk_fma_f32 v[38:39], v[204:205], v[182:183], v[38:39] op_sel_hi:[1,0,1]
	v_pk_fma_f32 v[28:29], v[206:207], v[182:183], v[28:29] op_sel_hi:[1,0,1]
	v_pk_fma_f32 v[36:37], v[208:209], v[182:183], v[36:37] op_sel:[0,1,0]
	v_pk_fma_f32 v[30:31], v[210:211], v[182:183], v[30:31] op_sel:[0,1,0]
	v_pk_fma_f32 v[38:39], v[212:213], v[182:183], v[38:39] op_sel:[0,1,0]
	v_pk_fma_f32 v[28:29], v[214:215], v[182:183], v[28:29] op_sel:[0,1,0]
	global_load_dwordx4 v[180:183], v[34:35], off offset:-8
	v_lshl_add_u64 v[116:117], v[32:33], 0, s[22:23]
	global_load_dwordx4 v[184:187], v[116:117], off
	global_load_dwordx4 v[188:191], v[116:117], off offset:16
	global_load_dwordx4 v[192:195], v[116:117], off offset:512
	global_load_dwordx4 v[196:199], v[116:117], off offset:528
	global_load_dwordx4 v[200:203], v[116:117], off offset:1024
	global_load_dwordx4 v[204:207], v[116:117], off offset:1040
	global_load_dwordx4 v[208:211], v[116:117], off offset:1536
	global_load_dwordx4 v[212:215], v[116:117], off offset:1552
	s_add_u32 s22, s22, 0x800
	s_addc_u32 s23, s23, 0
	v_lshl_add_u64 v[34:35], v[34:35], 0, 16
	s_waitcnt vmcnt(18)
	v_pk_fma_f32 v[36:37], v[84:85], v[80:81], v[36:37] op_sel_hi:[1,0,1]
	v_pk_fma_f32 v[30:31], v[86:87], v[80:81], v[30:31] op_sel_hi:[1,0,1]
	v_pk_fma_f32 v[38:39], v[88:89], v[80:81], v[38:39] op_sel_hi:[1,0,1]
	v_pk_fma_f32 v[28:29], v[90:91], v[80:81], v[28:29] op_sel_hi:[1,0,1]
	v_pk_fma_f32 v[36:37], v[92:93], v[80:81], v[36:37] op_sel:[0,1,0]
	v_pk_fma_f32 v[30:31], v[94:95], v[80:81], v[30:31] op_sel:[0,1,0]
	v_pk_fma_f32 v[38:39], v[96:97], v[80:81], v[38:39] op_sel:[0,1,0]
	v_pk_fma_f32 v[28:29], v[98:99], v[80:81], v[28:29] op_sel:[0,1,0]
	v_pk_fma_f32 v[36:37], v[100:101], v[82:83], v[36:37] op_sel_hi:[1,0,1]
	v_pk_fma_f32 v[30:31], v[102:103], v[82:83], v[30:31] op_sel_hi:[1,0,1]
	v_pk_fma_f32 v[38:39], v[104:105], v[82:83], v[38:39] op_sel_hi:[1,0,1]
	v_pk_fma_f32 v[28:29], v[106:107], v[82:83], v[28:29] op_sel_hi:[1,0,1]
	v_pk_fma_f32 v[36:37], v[108:109], v[82:83], v[36:37] op_sel:[0,1,0]
	v_pk_fma_f32 v[30:31], v[110:111], v[82:83], v[30:31] op_sel:[0,1,0]
	v_pk_fma_f32 v[38:39], v[112:113], v[82:83], v[38:39] op_sel:[0,1,0]
	v_pk_fma_f32 v[28:29], v[114:115], v[82:83], v[28:29] op_sel:[0,1,0]
	global_load_dwordx4 v[80:83], v[34:35], off offset:-8
	v_lshl_add_u64 v[116:117], v[32:33], 0, s[22:23]
	global_load_dwordx4 v[84:87], v[116:117], off
	global_load_dwordx4 v[88:91], v[116:117], off offset:16
	global_load_dwordx4 v[92:95], v[116:117], off offset:512
	global_load_dwordx4 v[96:99], v[116:117], off offset:528
	global_load_dwordx4 v[100:103], v[116:117], off offset:1024
	global_load_dwordx4 v[104:107], v[116:117], off offset:1040
	global_load_dwordx4 v[108:111], v[116:117], off offset:1536
	global_load_dwordx4 v[112:115], v[116:117], off offset:1552
	s_add_u32 s22, s22, 0x800
	s_addc_u32 s23, s23, 0
	v_lshl_add_u64 v[34:35], v[34:35], 0, 16
	s_waitcnt vmcnt(18)
	v_pk_fma_f32 v[36:37], v[148:149], v[144:145], v[36:37] op_sel_hi:[1,0,1]
	v_pk_fma_f32 v[30:31], v[150:151], v[144:145], v[30:31] op_sel_hi:[1,0,1]
	v_pk_fma_f32 v[38:39], v[152:153], v[144:145], v[38:39] op_sel_hi:[1,0,1]
	v_pk_fma_f32 v[28:29], v[154:155], v[144:145], v[28:29] op_sel_hi:[1,0,1]
	v_pk_fma_f32 v[36:37], v[156:157], v[144:145], v[36:37] op_sel:[0,1,0]
	v_pk_fma_f32 v[30:31], v[158:159], v[144:145], v[30:31] op_sel:[0,1,0]
	v_pk_fma_f32 v[38:39], v[160:161], v[144:145], v[38:39] op_sel:[0,1,0]
	v_pk_fma_f32 v[28:29], v[162:163], v[144:145], v[28:29] op_sel:[0,1,0]
	v_pk_fma_f32 v[36:37], v[164:165], v[146:147], v[36:37] op_sel_hi:[1,0,1]
	v_pk_fma_f32 v[30:31], v[166:167], v[146:147], v[30:31] op_sel_hi:[1,0,1]
	v_pk_fma_f32 v[38:39], v[168:169], v[146:147], v[38:39] op_sel_hi:[1,0,1]
	v_pk_fma_f32 v[28:29], v[170:171], v[146:147], v[28:29] op_sel_hi:[1,0,1]
	v_pk_fma_f32 v[36:37], v[172:173], v[146:147], v[36:37] op_sel:[0,1,0]
	v_pk_fma_f32 v[30:31], v[174:175], v[146:147], v[30:31] op_sel:[0,1,0]
	v_pk_fma_f32 v[38:39], v[176:177], v[146:147], v[38:39] op_sel:[0,1,0]
	v_pk_fma_f32 v[28:29], v[178:179], v[146:147], v[28:29] op_sel:[0,1,0]
	global_load_dwordx4 v[144:147], v[34:35], off offset:-8
	v_lshl_add_u64 v[116:117], v[32:33], 0, s[22:23]
	global_load_dwordx4 v[148:151], v[116:117], off
	global_load_dwordx4 v[152:155], v[116:117], off offset:16
	global_load_dwordx4 v[156:159], v[116:117], off offset:512
	global_load_dwordx4 v[160:163], v[116:117], off offset:528
	global_load_dwordx4 v[164:167], v[116:117], off offset:1024
	global_load_dwordx4 v[168:171], v[116:117], off offset:1040
	global_load_dwordx4 v[172:175], v[116:117], off offset:1536
	global_load_dwordx4 v[176:179], v[116:117], off offset:1552
	s_add_u32 s22, s22, 0x800
	s_addc_u32 s23, s23, 0
	v_lshl_add_u64 v[34:35], v[34:35], 0, 16
	s_waitcnt vmcnt(18)
; __device__ __forceinline__ void wcomb_item(const float* w_in, const float* wg, const float* ngain, bf16_t* WinT, int item, int lane) {
;     ...
; #pragma unroll 4
;     for (int cin = 0; cin < 128; ++cin) { const float av = ap[cin]; const f32x4 b0 = *(const f32x4*)(bp + (size_t)cin * 128), b1 = *(const f32x4*)(bp + (size_t)cin * 128 + 4); c0 += b0 * av; c1 += b1 * av; }
	v_pk_fma_f32 v[36:37], v[184:185], v[180:181], v[36:37] op_sel_hi:[1,0,1]
	v_pk_fma_f32 v[30:31], v[186:187], v[180:181], v[30:31] op_sel_hi:[1,0,1]
	v_pk_fma_f32 v[38:39], v[188:189], v[180:181], v[38:39] op_sel_hi:[1,0,1]
	v_pk_fma_f32 v[28:29], v[190:191], v[180:181], v[28:29] op_sel_hi:[1,0,1]
	v_pk_fma_f32 v[36:37], v[192:193], v[180:181], v[36:37] op_sel:[0,1,0]
	v_pk_fma_f32 v[30:31], v[194:195], v[180:181], v[30:31] op_sel:[0,1,0]
	v_pk_fma_f32 v[38:39], v[196:197], v[180:181], v[38:39] op_sel:[0,1,0]
	v_pk_fma_f32 v[28:29], v[198:199], v[180:181], v[28:29] op_sel:[0,1,0]
	v_pk_fma_f32 v[36:37], v[200:201], v[182:183], v[36:37] op_sel_hi:[1,0,1]
	v_pk_fma_f32 v[30:31], v[202:203], v[182:183], v[30:31] op_sel_hi:[1,0,1]
	v_pk_fma_f32 v[38:39], v[204:205], v[182:183], v[38:39] op_sel_hi:[1,0,1]
	v_pk_fma_f32 v[28:29], v[206:207], v[182:183], v[28:29] op_sel_hi:[1,0,1]
	v_pk_fma_f32 v[36:37], v[208:209], v[182:183], v[36:37] op_sel:[0,1,0]
	v_pk_fma_f32 v[30:31], v[210:211], v[182:183], v[30:31] op_sel:[0,1,0]
	v_pk_fma_f32 v[38:39], v[212:213], v[182:183], v[38:39] op_sel:[0,1,0]
	v_pk_fma_f32 v[28:29], v[214:215], v[182:183], v[28:29] op_sel:[0,1,0]
	global_load_dwordx4 v[180:183], v[34:35], off offset:-8
	v_lshl_add_u64 v[116:117], v[32:33], 0, s[22:23]
	global_load_dwordx4 v[184:187], v[116:117], off
	global_load_dwordx4 v[188:191], v[116:117], off offset:16
	global_load_dwordx4 v[192:195], v[116:117], off offset:512
	global_load_dwordx4 v[196:199], v[116:117], off offset:528
	global_load_dwordx4 v[200:203], v[116:117], off offset:1024
	global_load_dwordx4 v[204:207], v[116:117], off offset:1040
	global_load_dwordx4 v[208:211], v[116:117], off offset:1536
	global_load_dwordx4 v[212:215], v[116:117], off offset:1552
	s_add_u32 s22, s22, 0x800
	s_addc_u32 s23, s23, 0
	v_lshl_add_u64 v[34:35], v[34:35], 0, 16
	s_waitcnt vmcnt(18)
	v_pk_fma_f32 v[36:37], v[84:85], v[80:81], v[36:37] op_sel_hi:[1,0,1]
	v_pk_fma_f32 v[30:31], v[86:87], v[80:81], v[30:31] op_sel_hi:[1,0,1]
	v_pk_fma_f32 v[38:39], v[88:89], v[80:81], v[38:39] op_sel_hi:[1,0,1]
	v_pk_fma_f32 v[28:29], v[90:91], v[80:81], v[28:29] op_sel_hi:[1,0,1]
	v_pk_fma_f32 v[36:37], v[92:93], v[80:81], v[36:37] op_sel:[0,1,0]
	v_pk_fma_f32 v[30:31], v[94:95], v[80:81], v[30:31] op_sel:[0,1,0]
	v_pk_fma_f32 v[38:39], v[96:97], v[80:81], v[38:39] op_sel:[0,1,0]
	v_pk_fma_f32 v[28:29], v[98:99], v[80:81], v[28:29] op_sel:[0,1,0]
	v_pk_fma_f32 v[36:37], v[100:101], v[82:83], v[36:37] op_sel_hi:[1,0,1]
	v_pk_fma_f32 v[30:31], v[102:103], v[82:83], v[30:31] op_sel_hi:[1,0,1]
	v_pk_fma_f32 v[38:39], v[104:105], v[82:83], v[38:39] op_sel_hi:[1,0,1]
	v_pk_fma_f32 v[28:29], v[106:107], v[82:83], v[28:29] op_sel_hi:[1,0,1]
	v_pk_fma_f32 v[36:37], v[108:109], v[82:83], v[36:37] op_sel:[0,1,0]
	v_pk_fma_f32 v[30:31], v[110:111], v[82:83], v[30:31] op_sel:[0,1,0]
	v_pk_fma_f32 v[38:39], v[112:113], v[82:83], v[38:39] op_sel:[0,1,0]
	v_pk_fma_f32 v[28:29], v[114:115], v[82:83], v[28:29] op_sel:[0,1,0]
	global_load_dwordx4 v[80:83], v[34:35], off offset:-8
	v_lshl_add_u64 v[116:117], v[32:33], 0, s[22:23]
	global_load_dwordx4 v[84:87], v[116:117], off
	global_load_dwordx4 v[88:91], v[116:117], off offset:16
	global_load_dwordx4 v[92:95], v[116:117], off offset:512
	global_load_dwordx4 v[96:99], v[116:117], off offset:528
	global_load_dwordx4 v[100:103], v[116:117], off offset:1024
	global_load_dwordx4 v[104:107], v[116:117], off offset:1040
	global_load_dwordx4 v[108:111], v[116:117], off offset:1536
	global_load_dwordx4 v[112:115], v[116:117], off offset:1552
	s_add_u32 s22, s22, 0x800
	s_addc_u32 s23, s23, 0
	v_lshl_add_u64 v[34:35], v[34:35], 0, 16
	s_waitcnt vmcnt(18)
	v_pk_fma_f32 v[36:37], v[148:149], v[144:145], v[36:37] op_sel_hi:[1,0,1]
	v_pk_fma_f32 v[30:31], v[150:151], v[144:145], v[30:31] op_sel_hi:[1,0,1]
	v_pk_fma_f32 v[38:39], v[152:153], v[144:145], v[38:39] op_sel_hi:[1,0,1]
	v_pk_fma_f32 v[28:29], v[154:155], v[144:145], v[28:29] op_sel_hi:[1,0,1]
	v_pk_fma_f32 v[36:37], v[156:157], v[144:145], v[36:37] op_sel:[0,1,0]
	v_pk_fma_f32 v[30:31], v[158:159], v[144:145], v[30:31] op_sel:[0,1,0]
	v_pk_fma_f32 v[38:39], v[160:161], v[144:145], v[38:39] op_sel:[0,1,0]
	v_pk_fma_f32 v[28:29], v[162:163], v[144:145], v[28:29] op_sel:[0,1,0]
	v_pk_fma_f32 v[36:37], v[164:165], v[146:147], v[36:37] op_sel_hi:[1,0,1]
	v_pk_fma_f32 v[30:31], v[166:167], v[146:147], v[30:31] op_sel_hi:[1,0,1]
	v_pk_fma_f32 v[38:39], v[168:169], v[146:147], v[38:39] op_sel_hi:[1,0,1]
	v_pk_fma_f32 v[28:29], v[170:171], v[146:147], v[28:29] op_sel_hi:[1,0,1]
	v_pk_fma_f32 v[36:37], v[172:173], v[146:147], v[36:37] op_sel:[0,1,0]
	v_pk_fma_f32 v[30:31], v[174:175], v[146:147], v[30:31] op_sel:[0,1,0]
	v_pk_fma_f32 v[38:39], v[176:177], v[146:147], v[38:39] op_sel:[0,1,0]
	v_pk_fma_f32 v[28:29], v[178:179], v[146:147], v[28:29] op_sel:[0,1,0]
	global_load_dwordx4 v[144:147], v[34:35], off offset:-8
	v_lshl_add_u64 v[116:117], v[32:33], 0, s[22:23]
	global_load_dwordx4 v[148:151], v[116:117], off
	global_load_dwordx4 v[152:155], v[116:117], off offset:16
	global_load_dwordx4 v[156:159], v[116:117], off offset:512
	global_load_dwordx4 v[160:163], v[116:117], off offset:528
	global_load_dwordx4 v[164:167], v[116:117], off offset:1024
	global_load_dwordx4 v[168:171], v[116:117], off offset:1040
	global_load_dwordx4 v[172:175], v[116:117], off offset:1536
	global_load_dwordx4 v[176:179], v[116:117], off offset:1552
	s_add_u32 s22, s22, 0x800
	s_addc_u32 s23, s23, 0
	v_lshl_add_u64 v[34:35], v[34:35], 0, 16
	s_waitcnt vmcnt(18)
; __device__ __forceinline__ void wcomb_item(const float* w_in, const float* wg, const float* ngain, bf16_t* WinT, int item, int lane) {
;     ...
; #pragma unroll 4
;     for (int cin = 0; cin < 128; ++cin) { const float av = ap[cin]; const f32x4 b0 = *(const f32x4*)(bp + (size_t)cin * 128), b1 = *(const f32x4*)(bp + (size_t)cin * 128 + 4); c0 += b0 * av; c1 += b1 * av; }
	v_pk_fma_f32 v[36:37], v[184:185], v[180:181], v[36:37] op_sel_hi:[1,0,1]
	v_pk_fma_f32 v[30:31], v[186:187], v[180:181], v[30:31] op_sel_hi:[1,0,1]
	v_pk_fma_f32 v[38:39], v[188:189], v[180:181], v[38:39] op_sel_hi:[1,0,1]
	v_pk_fma_f32 v[28:29], v[190:191], v[180:181], v[28:29] op_sel_hi:[1,0,1]
	v_pk_fma_f32 v[36:37], v[192:193], v[180:181], v[36:37] op_sel:[0,1,0]
	v_pk_fma_f32 v[30:31], v[194:195], v[180:181], v[30:31] op_sel:[0,1,0]
	v_pk_fma_f32 v[38:39], v[196:197], v[180:181], v[38:39] op_sel:[0,1,0]
	v_pk_fma_f32 v[28:29], v[198:199], v[180:181], v[28:29] op_sel:[0,1,0]
	v_pk_fma_f32 v[36:37], v[200:201], v[182:183], v[36:37] op_sel_hi:[1,0,1]
	v_pk_fma_f32 v[30:31], v[202:203], v[182:183], v[30:31] op_sel_hi:[1,0,1]
	v_pk_fma_f32 v[38:39], v[204:205], v[182:183], v[38:39] op_sel_hi:[1,0,1]
	v_pk_fma_f32 v[28:29], v[206:207], v[182:183], v[28:29] op_sel_hi:[1,0,1]
	v_pk_fma_f32 v[36:37], v[208:209], v[182:183], v[36:37] op_sel:[0,1,0]
	v_pk_fma_f32 v[30:31], v[210:211], v[182:183], v[30:31] op_sel:[0,1,0]
	v_pk_fma_f32 v[38:39], v[212:213], v[182:183], v[38:39] op_sel:[0,1,0]
	v_pk_fma_f32 v[28:29], v[214:215], v[182:183], v[28:29] op_sel:[0,1,0]
	global_load_dwordx4 v[180:183], v[34:35], off offset:-8
	v_lshl_add_u64 v[116:117], v[32:33], 0, s[22:23]
	global_load_dwordx4 v[184:187], v[116:117], off
	global_load_dwordx4 v[188:191], v[116:117], off offset:16
	global_load_dwordx4 v[192:195], v[116:117], off offset:512
	global_load_dwordx4 v[196:199], v[116:117], off offset:528
	global_load_dwordx4 v[200:203], v[116:117], off offset:1024
	global_load_dwordx4 v[204:207], v[116:117], off offset:1040
	global_load_dwordx4 v[208:211], v[116:117], off offset:1536
	global_load_dwordx4 v[212:215], v[116:117], off offset:1552
	s_add_u32 s22, s22, 0x800
	s_addc_u32 s23, s23, 0
	v_lshl_add_u64 v[34:35], v[34:35], 0, 16
	s_waitcnt vmcnt(18)
	v_pk_fma_f32 v[36:37], v[84:85], v[80:81], v[36:37] op_sel_hi:[1,0,1]
	v_pk_fma_f32 v[30:31], v[86:87], v[80:81], v[30:31] op_sel_hi:[1,0,1]
	v_pk_fma_f32 v[38:39], v[88:89], v[80:81], v[38:39] op_sel_hi:[1,0,1]
	v_pk_fma_f32 v[28:29], v[90:91], v[80:81], v[28:29] op_sel_hi:[1,0,1]
	v_pk_fma_f32 v[36:37], v[92:93], v[80:81], v[36:37] op_sel:[0,1,0]
	v_pk_fma_f32 v[30:31], v[94:95], v[80:81], v[30:31] op_sel:[0,1,0]
	v_pk_fma_f32 v[38:39], v[96:97], v[80:81], v[38:39] op_sel:[0,1,0]
	v_pk_fma_f32 v[28:29], v[98:99], v[80:81], v[28:29] op_sel:[0,1,0]
	v_pk_fma_f32 v[36:37], v[100:101], v[82:83], v[36:37] op_sel_hi:[1,0,1]
	v_pk_fma_f32 v[30:31], v[102:103], v[82:83], v[30:31] op_sel_hi:[1,0,1]
	v_pk_fma_f32 v[38:39], v[104:105], v[82:83], v[38:39] op_sel_hi:[1,0,1]
	v_pk_fma_f32 v[28:29], v[106:107], v[82:83], v[28:29] op_sel_hi:[1,0,1]
	v_pk_fma_f32 v[36:37], v[108:109], v[82:83], v[36:37] op_sel:[0,1,0]
	v_pk_fma_f32 v[30:31], v[110:111], v[82:83], v[30:31] op_sel:[0,1,0]
	v_pk_fma_f32 v[38:39], v[112:113], v[82:83], v[38:39] op_sel:[0,1,0]
	v_pk_fma_f32 v[28:29], v[114:115], v[82:83], v[28:29] op_sel:[0,1,0]
	global_load_dwordx4 v[80:83], v[34:35], off offset:-8
	v_lshl_add_u64 v[116:117], v[32:33], 0, s[22:23]
	global_load_dwordx4 v[84:87], v[116:117], off
	global_load_dwordx4 v[88:91], v[116:117], off offset:16
	global_load_dwordx4 v[92:95], v[116:117], off offset:512
	global_load_dwordx4 v[96:99], v[116:117], off offset:528
	global_load_dwordx4 v[100:103], v[116:117], off offset:1024
	global_load_dwordx4 v[104:107], v[116:117], off offset:1040
	global_load_dwordx4 v[108:111], v[116:117], off offset:1536
	global_load_dwordx4 v[112:115], v[116:117], off offset:1552
	s_add_u32 s22, s22, 0x800
	s_addc_u32 s23, s23, 0
	v_lshl_add_u64 v[34:35], v[34:35], 0, 16
	s_waitcnt vmcnt(18)
	v_pk_fma_f32 v[36:37], v[148:149], v[144:145], v[36:37] op_sel_hi:[1,0,1]
	v_pk_fma_f32 v[30:31], v[150:151], v[144:145], v[30:31] op_sel_hi:[1,0,1]
	v_pk_fma_f32 v[38:39], v[152:153], v[144:145], v[38:39] op_sel_hi:[1,0,1]
	v_pk_fma_f32 v[28:29], v[154:155], v[144:145], v[28:29] op_sel_hi:[1,0,1]
	v_pk_fma_f32 v[36:37], v[156:157], v[144:145], v[36:37] op_sel:[0,1,0]
	v_pk_fma_f32 v[30:31], v[158:159], v[144:145], v[30:31] op_sel:[0,1,0]
	v_pk_fma_f32 v[38:39], v[160:161], v[144:145], v[38:39] op_sel:[0,1,0]
	v_pk_fma_f32 v[28:29], v[162:163], v[144:145], v[28:29] op_sel:[0,1,0]
	v_pk_fma_f32 v[36:37], v[164:165], v[146:147], v[36:37] op_sel_hi:[1,0,1]
	v_pk_fma_f32 v[30:31], v[166:167], v[146:147], v[30:31] op_sel_hi:[1,0,1]
	v_pk_fma_f32 v[38:39], v[168:169], v[146:147], v[38:39] op_sel_hi:[1,0,1]
	v_pk_fma_f32 v[28:29], v[170:171], v[146:147], v[28:29] op_sel_hi:[1,0,1]
	v_pk_fma_f32 v[36:37], v[172:173], v[146:147], v[36:37] op_sel:[0,1,0]
	v_pk_fma_f32 v[30:31], v[174:175], v[146:147], v[30:31] op_sel:[0,1,0]
	v_pk_fma_f32 v[38:39], v[176:177], v[146:147], v[38:39] op_sel:[0,1,0]
	v_pk_fma_f32 v[28:29], v[178:179], v[146:147], v[28:29] op_sel:[0,1,0]
	global_load_dwordx4 v[144:147], v[34:35], off offset:-8
	v_lshl_add_u64 v[116:117], v[32:33], 0, s[22:23]
	global_load_dwordx4 v[148:151], v[116:117], off
	global_load_dwordx4 v[152:155], v[116:117], off offset:16
	global_load_dwordx4 v[156:159], v[116:117], off offset:512
	global_load_dwordx4 v[160:163], v[116:117], off offset:528
	global_load_dwordx4 v[164:167], v[116:117], off offset:1024
	global_load_dwordx4 v[168:171], v[116:117], off offset:1040
	global_load_dwordx4 v[172:175], v[116:117], off offset:1536
	global_load_dwordx4 v[176:179], v[116:117], off offset:1552
	s_add_u32 s22, s22, 0x800
	s_addc_u32 s23, s23, 0
	v_lshl_add_u64 v[34:35], v[34:35], 0, 16
	s_waitcnt vmcnt(18)
; __device__ __forceinline__ void wcomb_item(const float* w_in, const float* wg, const float* ngain, bf16_t* WinT, int item, int lane) {
;     ...
; #pragma unroll 4
;     for (int cin = 0; cin < 128; ++cin) { const float av = ap[cin]; const f32x4 b0 = *(const f32x4*)(bp + (size_t)cin * 128), b1 = *(const f32x4*)(bp + (size_t)cin * 128 + 4); c0 += b0 * av; c1 += b1 * av; }
	v_pk_fma_f32 v[36:37], v[184:185], v[180:181], v[36:37] op_sel_hi:[1,0,1]
	v_pk_fma_f32 v[30:31], v[186:187], v[180:181], v[30:31] op_sel_hi:[1,0,1]
	v_pk_fma_f32 v[38:39], v[188:189], v[180:181], v[38:39] op_sel_hi:[1,0,1]
	v_pk_fma_f32 v[28:29], v[190:191], v[180:181], v[28:29] op_sel_hi:[1,0,1]
	v_pk_fma_f32 v[36:37], v[192:193], v[180:181], v[36:37] op_sel:[0,1,0]
	v_pk_fma_f32 v[30:31], v[194:195], v[180:181], v[30:31] op_sel:[0,1,0]
	v_pk_fma_f32 v[38:39], v[196:197], v[180:181], v[38:39] op_sel:[0,1,0]
	v_pk_fma_f32 v[28:29], v[198:199], v[180:181], v[28:29] op_sel:[0,1,0]
	v_pk_fma_f32 v[36:37], v[200:201], v[182:183], v[36:37] op_sel_hi:[1,0,1]
	v_pk_fma_f32 v[30:31], v[202:203], v[182:183], v[30:31] op_sel_hi:[1,0,1]
	v_pk_fma_f32 v[38:39], v[204:205], v[182:183], v[38:39] op_sel_hi:[1,0,1]
	v_pk_fma_f32 v[28:29], v[206:207], v[182:183], v[28:29] op_sel_hi:[1,0,1]
	v_pk_fma_f32 v[36:37], v[208:209], v[182:183], v[36:37] op_sel:[0,1,0]
	v_pk_fma_f32 v[30:31], v[210:211], v[182:183], v[30:31] op_sel:[0,1,0]
	v_pk_fma_f32 v[38:39], v[212:213], v[182:183], v[38:39] op_sel:[0,1,0]
	v_pk_fma_f32 v[28:29], v[214:215], v[182:183], v[28:29] op_sel:[0,1,0]
	global_load_dwordx4 v[180:183], v[34:35], off offset:-8
	v_lshl_add_u64 v[116:117], v[32:33], 0, s[22:23]
	global_load_dwordx4 v[184:187], v[116:117], off
	global_load_dwordx4 v[188:191], v[116:117], off offset:16
	global_load_dwordx4 v[192:195], v[116:117], off offset:512
	global_load_dwordx4 v[196:199], v[116:117], off offset:528
	global_load_dwordx4 v[200:203], v[116:117], off offset:1024
	global_load_dwordx4 v[204:207], v[116:117], off offset:1040
	global_load_dwordx4 v[208:211], v[116:117], off offset:1536
	global_load_dwordx4 v[212:215], v[116:117], off offset:1552
	s_add_u32 s22, s22, 0x800
	s_addc_u32 s23, s23, 0
	v_lshl_add_u64 v[34:35], v[34:35], 0, 16
	s_waitcnt vmcnt(18)
	v_pk_fma_f32 v[36:37], v[84:85], v[80:81], v[36:37] op_sel_hi:[1,0,1]
	v_pk_fma_f32 v[30:31], v[86:87], v[80:81], v[30:31] op_sel_hi:[1,0,1]
	v_pk_fma_f32 v[38:39], v[88:89], v[80:81], v[38:39] op_sel_hi:[1,0,1]
	v_pk_fma_f32 v[28:29], v[90:91], v[80:81], v[28:29] op_sel_hi:[1,0,1]
	v_pk_fma_f32 v[36:37], v[92:93], v[80:81], v[36:37] op_sel:[0,1,0]
	v_pk_fma_f32 v[30:31], v[94:95], v[80:81], v[30:31] op_sel:[0,1,0]
	v_pk_fma_f32 v[38:39], v[96:97], v[80:81], v[38:39] op_sel:[0,1,0]
	v_pk_fma_f32 v[28:29], v[98:99], v[80:81], v[28:29] op_sel:[0,1,0]
	v_pk_fma_f32 v[36:37], v[100:101], v[82:83], v[36:37] op_sel_hi:[1,0,1]
	v_pk_fma_f32 v[30:31], v[102:103], v[82:83], v[30:31] op_sel_hi:[1,0,1]
	v_pk_fma_f32 v[38:39], v[104:105], v[82:83], v[38:39] op_sel_hi:[1,0,1]
	v_pk_fma_f32 v[28:29], v[106:107], v[82:83], v[28:29] op_sel_hi:[1,0,1]
	v_pk_fma_f32 v[36:37], v[108:109], v[82:83], v[36:37] op_sel:[0,1,0]
	v_pk_fma_f32 v[30:31], v[110:111], v[82:83], v[30:31] op_sel:[0,1,0]
	v_pk_fma_f32 v[38:39], v[112:113], v[82:83], v[38:39] op_sel:[0,1,0]
	v_pk_fma_f32 v[28:29], v[114:115], v[82:83], v[28:29] op_sel:[0,1,0]
	global_load_dwordx4 v[80:83], v[34:35], off offset:-8
	v_lshl_add_u64 v[116:117], v[32:33], 0, s[22:23]
	global_load_dwordx4 v[84:87], v[116:117], off
	global_load_dwordx4 v[88:91], v[116:117], off offset:16
	global_load_dwordx4 v[92:95], v[116:117], off offset:512
	global_load_dwordx4 v[96:99], v[116:117], off offset:528
	global_load_dwordx4 v[100:103], v[116:117], off offset:1024
	global_load_dwordx4 v[104:107], v[116:117], off offset:1040
	global_load_dwordx4 v[108:111], v[116:117], off offset:1536
	global_load_dwordx4 v[112:115], v[116:117], off offset:1552
	s_add_u32 s22, s22, 0x800
	s_addc_u32 s23, s23, 0
	v_lshl_add_u64 v[34:35], v[34:35], 0, 16
	s_waitcnt vmcnt(18)
	v_pk_fma_f32 v[36:37], v[148:149], v[144:145], v[36:37] op_sel_hi:[1,0,1]
	v_pk_fma_f32 v[30:31], v[150:151], v[144:145], v[30:31] op_sel_hi:[1,0,1]
	v_pk_fma_f32 v[38:39], v[152:153], v[144:145], v[38:39] op_sel_hi:[1,0,1]
	v_pk_fma_f32 v[28:29], v[154:155], v[144:145], v[28:29] op_sel_hi:[1,0,1]
	v_pk_fma_f32 v[36:37], v[156:157], v[144:145], v[36:37] op_sel:[0,1,0]
	v_pk_fma_f32 v[30:31], v[158:159], v[144:145], v[30:31] op_sel:[0,1,0]
	v_pk_fma_f32 v[38:39], v[160:161], v[144:145], v[38:39] op_sel:[0,1,0]
	v_pk_fma_f32 v[28:29], v[162:163], v[144:145], v[28:29] op_sel:[0,1,0]
	v_pk_fma_f32 v[36:37], v[164:165], v[146:147], v[36:37] op_sel_hi:[1,0,1]
	v_pk_fma_f32 v[30:31], v[166:167], v[146:147], v[30:31] op_sel_hi:[1,0,1]
	v_pk_fma_f32 v[38:39], v[168:169], v[146:147], v[38:39] op_sel_hi:[1,0,1]
	v_pk_fma_f32 v[28:29], v[170:171], v[146:147], v[28:29] op_sel_hi:[1,0,1]
	v_pk_fma_f32 v[36:37], v[172:173], v[146:147], v[36:37] op_sel:[0,1,0]
	v_pk_fma_f32 v[30:31], v[174:175], v[146:147], v[30:31] op_sel:[0,1,0]
	v_pk_fma_f32 v[38:39], v[176:177], v[146:147], v[38:39] op_sel:[0,1,0]
	v_pk_fma_f32 v[28:29], v[178:179], v[146:147], v[28:29] op_sel:[0,1,0]
	global_load_dwordx4 v[144:147], v[34:35], off offset:-8
	v_lshl_add_u64 v[116:117], v[32:33], 0, s[22:23]
	global_load_dwordx4 v[148:151], v[116:117], off
	global_load_dwordx4 v[152:155], v[116:117], off offset:16
	global_load_dwordx4 v[156:159], v[116:117], off offset:512
	global_load_dwordx4 v[160:163], v[116:117], off offset:528
	global_load_dwordx4 v[164:167], v[116:117], off offset:1024
	global_load_dwordx4 v[168:171], v[116:117], off offset:1040
	global_load_dwordx4 v[172:175], v[116:117], off offset:1536
	global_load_dwordx4 v[176:179], v[116:117], off offset:1552
	s_add_u32 s22, s22, 0x800
	s_addc_u32 s23, s23, 0
	v_lshl_add_u64 v[34:35], v[34:35], 0, 16
	s_waitcnt vmcnt(18)
; __device__ __forceinline__ unsigned cvt_pk_bf16(float lo, float hi) { unsigned r; asm volatile("v_cvt_pk_bf16_f32 %0, %1, %2" : "=v"(r) : "v"(lo), "v"(hi)); return r; }
; __device__ __forceinline__ void wcomb_item(const float* w_in, const float* wg, const float* ngain, bf16_t* WinT, int item, int lane) {
;     ...
;     for (int cin = 0; cin < 128; ++cin) { const float av = ap[cin]; const f32x4 b0 = *(const f32x4*)(bp + (size_t)cin * 128), b1 = *(const f32x4*)(bp + (size_t)cin * 128 + 4); c0 += b0 * av; c1 += b1 * av; }
;     const float gn = ngain[k];
;     bf16_t* o = WinT + (size_t)(128 * g + d0) * 1024 + k;
; #pragma unroll
;     for (int i = 0; i < 4; ++i) { o[(size_t)i * 1024] = (bf16_t)(cvt_pk_bf16(c0[i] * gn, 0.f) & 0xffffu); o[(size_t)(4 + i) * 1024] = (bf16_t)(cvt_pk_bf16(c1[i] * gn, 0.f) & 0xffffu); }
	v_pk_fma_f32 v[36:37], v[184:185], v[180:181], v[36:37] op_sel_hi:[1,0,1]
	v_pk_fma_f32 v[30:31], v[186:187], v[180:181], v[30:31] op_sel_hi:[1,0,1]
	v_pk_fma_f32 v[38:39], v[188:189], v[180:181], v[38:39] op_sel_hi:[1,0,1]
	v_pk_fma_f32 v[28:29], v[190:191], v[180:181], v[28:29] op_sel_hi:[1,0,1]
	v_pk_fma_f32 v[36:37], v[192:193], v[180:181], v[36:37] op_sel:[0,1,0]
	v_pk_fma_f32 v[30:31], v[194:195], v[180:181], v[30:31] op_sel:[0,1,0]
	v_pk_fma_f32 v[38:39], v[196:197], v[180:181], v[38:39] op_sel:[0,1,0]
	v_pk_fma_f32 v[28:29], v[198:199], v[180:181], v[28:29] op_sel:[0,1,0]
	v_pk_fma_f32 v[36:37], v[200:201], v[182:183], v[36:37] op_sel_hi:[1,0,1]
	v_pk_fma_f32 v[30:31], v[202:203], v[182:183], v[30:31] op_sel_hi:[1,0,1]
	v_pk_fma_f32 v[38:39], v[204:205], v[182:183], v[38:39] op_sel_hi:[1,0,1]
	v_pk_fma_f32 v[28:29], v[206:207], v[182:183], v[28:29] op_sel_hi:[1,0,1]
	v_pk_fma_f32 v[36:37], v[208:209], v[182:183], v[36:37] op_sel:[0,1,0]
	v_pk_fma_f32 v[30:31], v[210:211], v[182:183], v[30:31] op_sel:[0,1,0]
	v_pk_fma_f32 v[38:39], v[212:213], v[182:183], v[38:39] op_sel:[0,1,0]
	v_pk_fma_f32 v[28:29], v[214:215], v[182:183], v[28:29] op_sel:[0,1,0]
	s_waitcnt vmcnt(9)
	v_pk_fma_f32 v[36:37], v[84:85], v[80:81], v[36:37] op_sel_hi:[1,0,1]
	v_pk_fma_f32 v[30:31], v[86:87], v[80:81], v[30:31] op_sel_hi:[1,0,1]
	v_pk_fma_f32 v[38:39], v[88:89], v[80:81], v[38:39] op_sel_hi:[1,0,1]
	v_pk_fma_f32 v[28:29], v[90:91], v[80:81], v[28:29] op_sel_hi:[1,0,1]
	v_pk_fma_f32 v[36:37], v[92:93], v[80:81], v[36:37] op_sel:[0,1,0]
	v_pk_fma_f32 v[30:31], v[94:95], v[80:81], v[30:31] op_sel:[0,1,0]
	v_pk_fma_f32 v[38:39], v[96:97], v[80:81], v[38:39] op_sel:[0,1,0]
	v_pk_fma_f32 v[28:29], v[98:99], v[80:81], v[28:29] op_sel:[0,1,0]
	v_pk_fma_f32 v[36:37], v[100:101], v[82:83], v[36:37] op_sel_hi:[1,0,1]
	v_pk_fma_f32 v[30:31], v[102:103], v[82:83], v[30:31] op_sel_hi:[1,0,1]
	v_pk_fma_f32 v[38:39], v[104:105], v[82:83], v[38:39] op_sel_hi:[1,0,1]
	v_pk_fma_f32 v[28:29], v[106:107], v[82:83], v[28:29] op_sel_hi:[1,0,1]
	v_pk_fma_f32 v[36:37], v[108:109], v[82:83], v[36:37] op_sel:[0,1,0]
	v_pk_fma_f32 v[30:31], v[110:111], v[82:83], v[30:31] op_sel:[0,1,0]
	v_pk_fma_f32 v[38:39], v[112:113], v[82:83], v[38:39] op_sel:[0,1,0]
	v_pk_fma_f32 v[28:29], v[114:115], v[82:83], v[28:29] op_sel:[0,1,0]
	s_waitcnt vmcnt(0)
	v_pk_fma_f32 v[36:37], v[148:149], v[144:145], v[36:37] op_sel_hi:[1,0,1]
	v_pk_fma_f32 v[30:31], v[150:151], v[144:145], v[30:31] op_sel_hi:[1,0,1]
	v_pk_fma_f32 v[38:39], v[152:153], v[144:145], v[38:39] op_sel_hi:[1,0,1]
	v_pk_fma_f32 v[28:29], v[154:155], v[144:145], v[28:29] op_sel_hi:[1,0,1]
	v_pk_fma_f32 v[36:37], v[156:157], v[144:145], v[36:37] op_sel:[0,1,0]
	v_pk_fma_f32 v[30:31], v[158:159], v[144:145], v[30:31] op_sel:[0,1,0]
	v_pk_fma_f32 v[38:39], v[160:161], v[144:145], v[38:39] op_sel:[0,1,0]
	v_pk_fma_f32 v[28:29], v[162:163], v[144:145], v[28:29] op_sel:[0,1,0]
	v_pk_fma_f32 v[36:37], v[164:165], v[146:147], v[36:37] op_sel_hi:[1,0,1]
	v_pk_fma_f32 v[30:31], v[166:167], v[146:147], v[30:31] op_sel_hi:[1,0,1]
	v_pk_fma_f32 v[38:39], v[168:169], v[146:147], v[38:39] op_sel_hi:[1,0,1]
	v_pk_fma_f32 v[28:29], v[170:171], v[146:147], v[28:29] op_sel_hi:[1,0,1]
	v_pk_fma_f32 v[36:37], v[172:173], v[146:147], v[36:37] op_sel:[0,1,0]
	v_pk_fma_f32 v[30:31], v[174:175], v[146:147], v[30:31] op_sel:[0,1,0]
	v_pk_fma_f32 v[38:39], v[176:177], v[146:147], v[38:39] op_sel:[0,1,0]
	v_pk_fma_f32 v[28:29], v[178:179], v[146:147], v[28:29] op_sel:[0,1,0]
	v_lshlrev_b32_e32 v0, 2, v5
	global_load_dword v41, v0, s[20:21]
	v_or_b32_e32 v32, s0, v40
	v_ashrrev_i32_e32 v33, 31, v32
	v_lshlrev_b64 v[32:33], 11, v[32:33]
	v_lshl_add_u64 v[32:33], s[48:49], 0, v[32:33]
	v_lshlrev_b32_e32 v0, 1, v5
	v_lshl_add_u64 v[32:33], v[32:33], 0, v[0:1]
	s_movk_i32 s0, 0x2000
	v_add_co_u32_e32 v34, vcc, s0, v32
	s_waitcnt vmcnt(0)
	v_mul_f32_e32 v0, v36, v41
	v_cvt_pk_bf16_f32 v0, v0, v1
	global_store_short v[32:33], v0, off
	v_mul_f32_e32 v0, v38, v41
	v_cvt_pk_bf16_f32 v0, v0, v1
	v_addc_co_u32_e32 v35, vcc, 0, v33, vcc
	global_store_short v[34:35], v0, off
	v_mul_f32_e32 v0, v37, v41
	v_cvt_pk_bf16_f32 v0, v0, v1
	global_store_short v[32:33], v0, off offset:2048
	v_mul_f32_e32 v0, v39, v41
	v_cvt_pk_bf16_f32 v0, v0, v1
	global_store_short v[34:35], v0, off offset:2048
	v_mul_f32_e32 v0, v30, v41
	v_add_co_u32_e32 v34, vcc, s98, v32
	v_cvt_pk_bf16_f32 v0, v0, v1
	s_nop 1
	v_addc_co_u32_e32 v35, vcc, 0, v33, vcc
	global_store_short v[34:35], v0, off
	v_mul_f32_e32 v0, v28, v41
	v_add_co_u32_e32 v32, vcc, 0x3000, v32
	v_cvt_pk_bf16_f32 v0, v0, v1
	s_nop 1
	v_addc_co_u32_e32 v33, vcc, 0, v33, vcc
	global_store_short v[32:33], v0, off
	v_mul_f32_e32 v0, v31, v41
	v_cvt_pk_bf16_f32 v0, v0, v1
	global_store_short v[34:35], v0, off offset:2048
	v_mul_f32_e32 v0, v29, v41
	v_cvt_pk_bf16_f32 v0, v0, v1
	global_store_short v[32:33], v0, off offset:2048
	s_branch .LBB0_634

; __device__ __forceinline__ void wcomb_item(const float* w_in, const float* wg, const float* ngain, bf16_t* WinT, int item, int lane) {
;     ...
;     const float* ap = w_in + (size_t)k * DIN + 128 * g; const float* bp = wg + (size_t)g * 128 * 128 + d0;
;     f32x4 c0 = (f32x4){0.f, 0.f, 0.f, 0.f}, c1 = c0;
; #pragma unroll 4
;     for (int cin = 0; cin < 128; ++cin) { const float av = ap[cin]; const f32x4 b0 = *(const f32x4*)(bp + (size_t)cin * 128), b1 = *(const f32x4*)(bp + (size_t)cin * 128 + 4); c0 += b0 * av; c1 += b1 * av; }
.LBB0_815:
	global_load_dwordx4 v[80:83], v[20:21], off offset:-8
	v_lshl_add_u64 v[116:117], v[18:19], 0, s[6:7]
	global_load_dwordx4 v[84:87], v[116:117], off
	global_load_dwordx4 v[88:91], v[116:117], off offset:16
	global_load_dwordx4 v[92:95], v[116:117], off offset:512
	global_load_dwordx4 v[96:99], v[116:117], off offset:528
	global_load_dwordx4 v[100:103], v[116:117], off offset:1024
	global_load_dwordx4 v[104:107], v[116:117], off offset:1040
	global_load_dwordx4 v[108:111], v[116:117], off offset:1536
	global_load_dwordx4 v[112:115], v[116:117], off offset:1552
	s_add_u32 s6, s6, 0x800
	s_addc_u32 s7, s7, 0
	v_lshl_add_u64 v[20:21], v[20:21], 0, 16
	global_load_dwordx4 v[144:147], v[20:21], off offset:-8
	v_lshl_add_u64 v[116:117], v[18:19], 0, s[6:7]
	global_load_dwordx4 v[148:151], v[116:117], off
	global_load_dwordx4 v[152:155], v[116:117], off offset:16
	global_load_dwordx4 v[156:159], v[116:117], off offset:512
	global_load_dwordx4 v[160:163], v[116:117], off offset:528
	global_load_dwordx4 v[164:167], v[116:117], off offset:1024
	global_load_dwordx4 v[168:171], v[116:117], off offset:1040
	global_load_dwordx4 v[172:175], v[116:117], off offset:1536
	global_load_dwordx4 v[176:179], v[116:117], off offset:1552
	s_add_u32 s6, s6, 0x800
	s_addc_u32 s7, s7, 0
	v_lshl_add_u64 v[20:21], v[20:21], 0, 16
	global_load_dwordx4 v[180:183], v[20:21], off offset:-8
	v_lshl_add_u64 v[116:117], v[18:19], 0, s[6:7]
	global_load_dwordx4 v[184:187], v[116:117], off
	global_load_dwordx4 v[188:191], v[116:117], off offset:16
	global_load_dwordx4 v[192:195], v[116:117], off offset:512
	global_load_dwordx4 v[196:199], v[116:117], off offset:528
	global_load_dwordx4 v[200:203], v[116:117], off offset:1024
	global_load_dwordx4 v[204:207], v[116:117], off offset:1040
	global_load_dwordx4 v[208:211], v[116:117], off offset:1536
	global_load_dwordx4 v[212:215], v[116:117], off offset:1552
	s_add_u32 s6, s6, 0x800
	s_addc_u32 s7, s7, 0
	v_lshl_add_u64 v[20:21], v[20:21], 0, 16
	s_waitcnt vmcnt(18)
	v_pk_fma_f32 v[12:13], v[84:85], v[80:81], v[12:13] op_sel_hi:[1,0,1]
	v_pk_fma_f32 v[8:9], v[86:87], v[80:81], v[8:9] op_sel_hi:[1,0,1]
	v_pk_fma_f32 v[14:15], v[88:89], v[80:81], v[14:15] op_sel_hi:[1,0,1]
	v_pk_fma_f32 v[10:11], v[90:91], v[80:81], v[10:11] op_sel_hi:[1,0,1]
	v_pk_fma_f32 v[12:13], v[92:93], v[80:81], v[12:13] op_sel:[0,1,0]
	v_pk_fma_f32 v[8:9], v[94:95], v[80:81], v[8:9] op_sel:[0,1,0]
	v_pk_fma_f32 v[14:15], v[96:97], v[80:81], v[14:15] op_sel:[0,1,0]
	v_pk_fma_f32 v[10:11], v[98:99], v[80:81], v[10:11] op_sel:[0,1,0]
	v_pk_fma_f32 v[12:13], v[100:101], v[82:83], v[12:13] op_sel_hi:[1,0,1]
	v_pk_fma_f32 v[8:9], v[102:103], v[82:83], v[8:9] op_sel_hi:[1,0,1]
	v_pk_fma_f32 v[14:15], v[104:105], v[82:83], v[14:15] op_sel_hi:[1,0,1]
	v_pk_fma_f32 v[10:11], v[106:107], v[82:83], v[10:11] op_sel_hi:[1,0,1]
	v_pk_fma_f32 v[12:13], v[108:109], v[82:83], v[12:13] op_sel:[0,1,0]
	v_pk_fma_f32 v[8:9], v[110:111], v[82:83], v[8:9] op_sel:[0,1,0]
	v_pk_fma_f32 v[14:15], v[112:113], v[82:83], v[14:15] op_sel:[0,1,0]
	v_pk_fma_f32 v[10:11], v[114:115], v[82:83], v[10:11] op_sel:[0,1,0]
	global_load_dwordx4 v[80:83], v[20:21], off offset:-8
	v_lshl_add_u64 v[116:117], v[18:19], 0, s[6:7]
	global_load_dwordx4 v[84:87], v[116:117], off
	global_load_dwordx4 v[88:91], v[116:117], off offset:16
	global_load_dwordx4 v[92:95], v[116:117], off offset:512
	global_load_dwordx4 v[96:99], v[116:117], off offset:528
	global_load_dwordx4 v[100:103], v[116:117], off offset:1024
	global_load_dwordx4 v[104:107], v[116:117], off offset:1040
	global_load_dwordx4 v[108:111], v[116:117], off offset:1536
	global_load_dwordx4 v[112:115], v[116:117], off offset:1552
	s_add_u32 s6, s6, 0x800
	s_addc_u32 s7, s7, 0
	v_lshl_add_u64 v[20:21], v[20:21], 0, 16
	s_waitcnt vmcnt(18)
	v_pk_fma_f32 v[12:13], v[148:149], v[144:145], v[12:13] op_sel_hi:[1,0,1]
	v_pk_fma_f32 v[8:9], v[150:151], v[144:145], v[8:9] op_sel_hi:[1,0,1]
	v_pk_fma_f32 v[14:15], v[152:153], v[144:145], v[14:15] op_sel_hi:[1,0,1]
	v_pk_fma_f32 v[10:11], v[154:155], v[144:145], v[10:11] op_sel_hi:[1,0,1]
	v_pk_fma_f32 v[12:13], v[156:157], v[144:145], v[12:13] op_sel:[0,1,0]
	v_pk_fma_f32 v[8:9], v[158:159], v[144:145], v[8:9] op_sel:[0,1,0]
	v_pk_fma_f32 v[14:15], v[160:161], v[144:145], v[14:15] op_sel:[0,1,0]
	v_pk_fma_f32 v[10:11], v[162:163], v[144:145], v[10:11] op_sel:[0,1,0]
	v_pk_fma_f32 v[12:13], v[164:165], v[146:147], v[12:13] op_sel_hi:[1,0,1]
	v_pk_fma_f32 v[8:9], v[166:167], v[146:147], v[8:9] op_sel_hi:[1,0,1]
	v_pk_fma_f32 v[14:15], v[168:169], v[146:147], v[14:15] op_sel_hi:[1,0,1]
	v_pk_fma_f32 v[10:11], v[170:171], v[146:147], v[10:11] op_sel_hi:[1,0,1]
	v_pk_fma_f32 v[12:13], v[172:173], v[146:147], v[12:13] op_sel:[0,1,0]
	v_pk_fma_f32 v[8:9], v[174:175], v[146:147], v[8:9] op_sel:[0,1,0]
	v_pk_fma_f32 v[14:15], v[176:177], v[146:147], v[14:15] op_sel:[0,1,0]
	v_pk_fma_f32 v[10:11], v[178:179], v[146:147], v[10:11] op_sel:[0,1,0]
	global_load_dwordx4 v[144:147], v[20:21], off offset:-8
	v_lshl_add_u64 v[116:117], v[18:19], 0, s[6:7]
	global_load_dwordx4 v[148:151], v[116:117], off
	global_load_dwordx4 v[152:155], v[116:117], off offset:16
	global_load_dwordx4 v[156:159], v[116:117], off offset:512
	global_load_dwordx4 v[160:163], v[116:117], off offset:528
	global_load_dwordx4 v[164:167], v[116:117], off offset:1024
	global_load_dwordx4 v[168:171], v[116:117], off offset:1040
	global_load_dwordx4 v[172:175], v[116:117], off offset:1536
	global_load_dwordx4 v[176:179], v[116:117], off offset:1552
	s_add_u32 s6, s6, 0x800
	s_addc_u32 s7, s7, 0
	v_lshl_add_u64 v[20:21], v[20:21], 0, 16
	s_waitcnt vmcnt(18)
; __device__ __forceinline__ void wcomb_item(const float* w_in, const float* wg, const float* ngain, bf16_t* WinT, int item, int lane) {
;     ...
; #pragma unroll 4
;     for (int cin = 0; cin < 128; ++cin) { const float av = ap[cin]; const f32x4 b0 = *(const f32x4*)(bp + (size_t)cin * 128), b1 = *(const f32x4*)(bp + (size_t)cin * 128 + 4); c0 += b0 * av; c1 += b1 * av; }
	v_pk_fma_f32 v[12:13], v[184:185], v[180:181], v[12:13] op_sel_hi:[1,0,1]
	v_pk_fma_f32 v[8:9], v[186:187], v[180:181], v[8:9] op_sel_hi:[1,0,1]
	v_pk_fma_f32 v[14:15], v[188:189], v[180:181], v[14:15] op_sel_hi:[1,0,1]
	v_pk_fma_f32 v[10:11], v[190:191], v[180:181], v[10:11] op_sel_hi:[1,0,1]
	v_pk_fma_f32 v[12:13], v[192:193], v[180:181], v[12:13] op_sel:[0,1,0]
	v_pk_fma_f32 v[8:9], v[194:195], v[180:181], v[8:9] op_sel:[0,1,0]
	v_pk_fma_f32 v[14:15], v[196:197], v[180:181], v[14:15] op_sel:[0,1,0]
	v_pk_fma_f32 v[10:11], v[198:199], v[180:181], v[10:11] op_sel:[0,1,0]
	v_pk_fma_f32 v[12:13], v[200:201], v[182:183], v[12:13] op_sel_hi:[1,0,1]
	v_pk_fma_f32 v[8:9], v[202:203], v[182:183], v[8:9] op_sel_hi:[1,0,1]
	v_pk_fma_f32 v[14:15], v[204:205], v[182:183], v[14:15] op_sel_hi:[1,0,1]
	v_pk_fma_f32 v[10:11], v[206:207], v[182:183], v[10:11] op_sel_hi:[1,0,1]
	v_pk_fma_f32 v[12:13], v[208:209], v[182:183], v[12:13] op_sel:[0,1,0]
	v_pk_fma_f32 v[8:9], v[210:211], v[182:183], v[8:9] op_sel:[0,1,0]
	v_pk_fma_f32 v[14:15], v[212:213], v[182:183], v[14:15] op_sel:[0,1,0]
	v_pk_fma_f32 v[10:11], v[214:215], v[182:183], v[10:11] op_sel:[0,1,0]
	global_load_dwordx4 v[180:183], v[20:21], off offset:-8
	v_lshl_add_u64 v[116:117], v[18:19], 0, s[6:7]
	global_load_dwordx4 v[184:187], v[116:117], off
	global_load_dwordx4 v[188:191], v[116:117], off offset:16
	global_load_dwordx4 v[192:195], v[116:117], off offset:512
	global_load_dwordx4 v[196:199], v[116:117], off offset:528
	global_load_dwordx4 v[200:203], v[116:117], off offset:1024
	global_load_dwordx4 v[204:207], v[116:117], off offset:1040
	global_load_dwordx4 v[208:211], v[116:117], off offset:1536
	global_load_dwordx4 v[212:215], v[116:117], off offset:1552
	s_add_u32 s6, s6, 0x800
	s_addc_u32 s7, s7, 0
	v_lshl_add_u64 v[20:21], v[20:21], 0, 16
	s_waitcnt vmcnt(18)
	v_pk_fma_f32 v[12:13], v[84:85], v[80:81], v[12:13] op_sel_hi:[1,0,1]
	v_pk_fma_f32 v[8:9], v[86:87], v[80:81], v[8:9] op_sel_hi:[1,0,1]
	v_pk_fma_f32 v[14:15], v[88:89], v[80:81], v[14:15] op_sel_hi:[1,0,1]
	v_pk_fma_f32 v[10:11], v[90:91], v[80:81], v[10:11] op_sel_hi:[1,0,1]
	v_pk_fma_f32 v[12:13], v[92:93], v[80:81], v[12:13] op_sel:[0,1,0]
	v_pk_fma_f32 v[8:9], v[94:95], v[80:81], v[8:9] op_sel:[0,1,0]
	v_pk_fma_f32 v[14:15], v[96:97], v[80:81], v[14:15] op_sel:[0,1,0]
	v_pk_fma_f32 v[10:11], v[98:99], v[80:81], v[10:11] op_sel:[0,1,0]
	v_pk_fma_f32 v[12:13], v[100:101], v[82:83], v[12:13] op_sel_hi:[1,0,1]
	v_pk_fma_f32 v[8:9], v[102:103], v[82:83], v[8:9] op_sel_hi:[1,0,1]
	v_pk_fma_f32 v[14:15], v[104:105], v[82:83], v[14:15] op_sel_hi:[1,0,1]
	v_pk_fma_f32 v[10:11], v[106:107], v[82:83], v[10:11] op_sel_hi:[1,0,1]
	v_pk_fma_f32 v[12:13], v[108:109], v[82:83], v[12:13] op_sel:[0,1,0]
	v_pk_fma_f32 v[8:9], v[110:111], v[82:83], v[8:9] op_sel:[0,1,0]
	v_pk_fma_f32 v[14:15], v[112:113], v[82:83], v[14:15] op_sel:[0,1,0]
	v_pk_fma_f32 v[10:11], v[114:115], v[82:83], v[10:11] op_sel:[0,1,0]
	global_load_dwordx4 v[80:83], v[20:21], off offset:-8
	v_lshl_add_u64 v[116:117], v[18:19], 0, s[6:7]
	global_load_dwordx4 v[84:87], v[116:117], off
	global_load_dwordx4 v[88:91], v[116:117], off offset:16
	global_load_dwordx4 v[92:95], v[116:117], off offset:512
	global_load_dwordx4 v[96:99], v[116:117], off offset:528
	global_load_dwordx4 v[100:103], v[116:117], off offset:1024
	global_load_dwordx4 v[104:107], v[116:117], off offset:1040
	global_load_dwordx4 v[108:111], v[116:117], off offset:1536
	global_load_dwordx4 v[112:115], v[116:117], off offset:1552
	s_add_u32 s6, s6, 0x800
	s_addc_u32 s7, s7, 0
	v_lshl_add_u64 v[20:21], v[20:21], 0, 16
	s_waitcnt vmcnt(18)
	v_pk_fma_f32 v[12:13], v[148:149], v[144:145], v[12:13] op_sel_hi:[1,0,1]
	v_pk_fma_f32 v[8:9], v[150:151], v[144:145], v[8:9] op_sel_hi:[1,0,1]
	v_pk_fma_f32 v[14:15], v[152:153], v[144:145], v[14:15] op_sel_hi:[1,0,1]
	v_pk_fma_f32 v[10:11], v[154:155], v[144:145], v[10:11] op_sel_hi:[1,0,1]
	v_pk_fma_f32 v[12:13], v[156:157], v[144:145], v[12:13] op_sel:[0,1,0]
	v_pk_fma_f32 v[8:9], v[158:159], v[144:145], v[8:9] op_sel:[0,1,0]
	v_pk_fma_f32 v[14:15], v[160:161], v[144:145], v[14:15] op_sel:[0,1,0]
	v_pk_fma_f32 v[10:11], v[162:163], v[144:145], v[10:11] op_sel:[0,1,0]
	v_pk_fma_f32 v[12:13], v[164:165], v[146:147], v[12:13] op_sel_hi:[1,0,1]
	v_pk_fma_f32 v[8:9], v[166:167], v[146:147], v[8:9] op_sel_hi:[1,0,1]
	v_pk_fma_f32 v[14:15], v[168:169], v[146:147], v[14:15] op_sel_hi:[1,0,1]
	v_pk_fma_f32 v[10:11], v[170:171], v[146:147], v[10:11] op_sel_hi:[1,0,1]
	v_pk_fma_f32 v[12:13], v[172:173], v[146:147], v[12:13] op_sel:[0,1,0]
	v_pk_fma_f32 v[8:9], v[174:175], v[146:147], v[8:9] op_sel:[0,1,0]
	v_pk_fma_f32 v[14:15], v[176:177], v[146:147], v[14:15] op_sel:[0,1,0]
	v_pk_fma_f32 v[10:11], v[178:179], v[146:147], v[10:11] op_sel:[0,1,0]
	global_load_dwordx4 v[144:147], v[20:21], off offset:-8
	v_lshl_add_u64 v[116:117], v[18:19], 0, s[6:7]
	global_load_dwordx4 v[148:151], v[116:117], off
	global_load_dwordx4 v[152:155], v[116:117], off offset:16
	global_load_dwordx4 v[156:159], v[116:117], off offset:512
	global_load_dwordx4 v[160:163], v[116:117], off offset:528
	global_load_dwordx4 v[164:167], v[116:117], off offset:1024
	global_load_dwordx4 v[168:171], v[116:117], off offset:1040
	global_load_dwordx4 v[172:175], v[116:117], off offset:1536
	global_load_dwordx4 v[176:179], v[116:117], off offset:1552
	s_add_u32 s6, s6, 0x800
	s_addc_u32 s7, s7, 0
	v_lshl_add_u64 v[20:21], v[20:21], 0, 16
	s_waitcnt vmcnt(18)
; __device__ __forceinline__ void wcomb_item(const float* w_in, const float* wg, const float* ngain, bf16_t* WinT, int item, int lane) {
;     ...
; #pragma unroll 4
;     for (int cin = 0; cin < 128; ++cin) { const float av = ap[cin]; const f32x4 b0 = *(const f32x4*)(bp + (size_t)cin * 128), b1 = *(const f32x4*)(bp + (size_t)cin * 128 + 4); c0 += b0 * av; c1 += b1 * av; }
	v_pk_fma_f32 v[12:13], v[184:185], v[180:181], v[12:13] op_sel_hi:[1,0,1]
	v_pk_fma_f32 v[8:9], v[186:187], v[180:181], v[8:9] op_sel_hi:[1,0,1]
	v_pk_fma_f32 v[14:15], v[188:189], v[180:181], v[14:15] op_sel_hi:[1,0,1]
	v_pk_fma_f32 v[10:11], v[190:191], v[180:181], v[10:11] op_sel_hi:[1,0,1]
	v_pk_fma_f32 v[12:13], v[192:193], v[180:181], v[12:13] op_sel:[0,1,0]
	v_pk_fma_f32 v[8:9], v[194:195], v[180:181], v[8:9] op_sel:[0,1,0]
	v_pk_fma_f32 v[14:15], v[196:197], v[180:181], v[14:15] op_sel:[0,1,0]
	v_pk_fma_f32 v[10:11], v[198:199], v[180:181], v[10:11] op_sel:[0,1,0]
	v_pk_fma_f32 v[12:13], v[200:201], v[182:183], v[12:13] op_sel_hi:[1,0,1]
	v_pk_fma_f32 v[8:9], v[202:203], v[182:183], v[8:9] op_sel_hi:[1,0,1]
	v_pk_fma_f32 v[14:15], v[204:205], v[182:183], v[14:15] op_sel_hi:[1,0,1]
	v_pk_fma_f32 v[10:11], v[206:207], v[182:183], v[10:11] op_sel_hi:[1,0,1]
	v_pk_fma_f32 v[12:13], v[208:209], v[182:183], v[12:13] op_sel:[0,1,0]
	v_pk_fma_f32 v[8:9], v[210:211], v[182:183], v[8:9] op_sel:[0,1,0]
	v_pk_fma_f32 v[14:15], v[212:213], v[182:183], v[14:15] op_sel:[0,1,0]
	v_pk_fma_f32 v[10:11], v[214:215], v[182:183], v[10:11] op_sel:[0,1,0]
	global_load_dwordx4 v[180:183], v[20:21], off offset:-8
	v_lshl_add_u64 v[116:117], v[18:19], 0, s[6:7]
	global_load_dwordx4 v[184:187], v[116:117], off
	global_load_dwordx4 v[188:191], v[116:117], off offset:16
	global_load_dwordx4 v[192:195], v[116:117], off offset:512
	global_load_dwordx4 v[196:199], v[116:117], off offset:528
	global_load_dwordx4 v[200:203], v[116:117], off offset:1024
	global_load_dwordx4 v[204:207], v[116:117], off offset:1040
	global_load_dwordx4 v[208:211], v[116:117], off offset:1536
	global_load_dwordx4 v[212:215], v[116:117], off offset:1552
	s_add_u32 s6, s6, 0x800
	s_addc_u32 s7, s7, 0
	v_lshl_add_u64 v[20:21], v[20:21], 0, 16
	s_waitcnt vmcnt(18)
	v_pk_fma_f32 v[12:13], v[84:85], v[80:81], v[12:13] op_sel_hi:[1,0,1]
	v_pk_fma_f32 v[8:9], v[86:87], v[80:81], v[8:9] op_sel_hi:[1,0,1]
	v_pk_fma_f32 v[14:15], v[88:89], v[80:81], v[14:15] op_sel_hi:[1,0,1]
	v_pk_fma_f32 v[10:11], v[90:91], v[80:81], v[10:11] op_sel_hi:[1,0,1]
	v_pk_fma_f32 v[12:13], v[92:93], v[80:81], v[12:13] op_sel:[0,1,0]
	v_pk_fma_f32 v[8:9], v[94:95], v[80:81], v[8:9] op_sel:[0,1,0]
	v_pk_fma_f32 v[14:15], v[96:97], v[80:81], v[14:15] op_sel:[0,1,0]
	v_pk_fma_f32 v[10:11], v[98:99], v[80:81], v[10:11] op_sel:[0,1,0]
	v_pk_fma_f32 v[12:13], v[100:101], v[82:83], v[12:13] op_sel_hi:[1,0,1]
	v_pk_fma_f32 v[8:9], v[102:103], v[82:83], v[8:9] op_sel_hi:[1,0,1]
	v_pk_fma_f32 v[14:15], v[104:105], v[82:83], v[14:15] op_sel_hi:[1,0,1]
	v_pk_fma_f32 v[10:11], v[106:107], v[82:83], v[10:11] op_sel_hi:[1,0,1]
	v_pk_fma_f32 v[12:13], v[108:109], v[82:83], v[12:13] op_sel:[0,1,0]
	v_pk_fma_f32 v[8:9], v[110:111], v[82:83], v[8:9] op_sel:[0,1,0]
	v_pk_fma_f32 v[14:15], v[112:113], v[82:83], v[14:15] op_sel:[0,1,0]
	v_pk_fma_f32 v[10:11], v[114:115], v[82:83], v[10:11] op_sel:[0,1,0]
	global_load_dwordx4 v[80:83], v[20:21], off offset:-8
	v_lshl_add_u64 v[116:117], v[18:19], 0, s[6:7]
	global_load_dwordx4 v[84:87], v[116:117], off
	global_load_dwordx4 v[88:91], v[116:117], off offset:16
	global_load_dwordx4 v[92:95], v[116:117], off offset:512
	global_load_dwordx4 v[96:99], v[116:117], off offset:528
	global_load_dwordx4 v[100:103], v[116:117], off offset:1024
	global_load_dwordx4 v[104:107], v[116:117], off offset:1040
	global_load_dwordx4 v[108:111], v[116:117], off offset:1536
	global_load_dwordx4 v[112:115], v[116:117], off offset:1552
	s_add_u32 s6, s6, 0x800
	s_addc_u32 s7, s7, 0
	v_lshl_add_u64 v[20:21], v[20:21], 0, 16
	s_waitcnt vmcnt(18)
	v_pk_fma_f32 v[12:13], v[148:149], v[144:145], v[12:13] op_sel_hi:[1,0,1]
	v_pk_fma_f32 v[8:9], v[150:151], v[144:145], v[8:9] op_sel_hi:[1,0,1]
	v_pk_fma_f32 v[14:15], v[152:153], v[144:145], v[14:15] op_sel_hi:[1,0,1]
	v_pk_fma_f32 v[10:11], v[154:155], v[144:145], v[10:11] op_sel_hi:[1,0,1]
	v_pk_fma_f32 v[12:13], v[156:157], v[144:145], v[12:13] op_sel:[0,1,0]
	v_pk_fma_f32 v[8:9], v[158:159], v[144:145], v[8:9] op_sel:[0,1,0]
	v_pk_fma_f32 v[14:15], v[160:161], v[144:145], v[14:15] op_sel:[0,1,0]
	v_pk_fma_f32 v[10:11], v[162:163], v[144:145], v[10:11] op_sel:[0,1,0]
	v_pk_fma_f32 v[12:13], v[164:165], v[146:147], v[12:13] op_sel_hi:[1,0,1]
	v_pk_fma_f32 v[8:9], v[166:167], v[146:147], v[8:9] op_sel_hi:[1,0,1]
	v_pk_fma_f32 v[14:15], v[168:169], v[146:147], v[14:15] op_sel_hi:[1,0,1]
	v_pk_fma_f32 v[10:11], v[170:171], v[146:147], v[10:11] op_sel_hi:[1,0,1]
	v_pk_fma_f32 v[12:13], v[172:173], v[146:147], v[12:13] op_sel:[0,1,0]
	v_pk_fma_f32 v[8:9], v[174:175], v[146:147], v[8:9] op_sel:[0,1,0]
	v_pk_fma_f32 v[14:15], v[176:177], v[146:147], v[14:15] op_sel:[0,1,0]
	v_pk_fma_f32 v[10:11], v[178:179], v[146:147], v[10:11] op_sel:[0,1,0]
	global_load_dwordx4 v[144:147], v[20:21], off offset:-8
	v_lshl_add_u64 v[116:117], v[18:19], 0, s[6:7]
	global_load_dwordx4 v[148:151], v[116:117], off
	global_load_dwordx4 v[152:155], v[116:117], off offset:16
	global_load_dwordx4 v[156:159], v[116:117], off offset:512
	global_load_dwordx4 v[160:163], v[116:117], off offset:528
	global_load_dwordx4 v[164:167], v[116:117], off offset:1024
	global_load_dwordx4 v[168:171], v[116:117], off offset:1040
	global_load_dwordx4 v[172:175], v[116:117], off offset:1536
	global_load_dwordx4 v[176:179], v[116:117], off offset:1552
	s_add_u32 s6, s6, 0x800
	s_addc_u32 s7, s7, 0
	v_lshl_add_u64 v[20:21], v[20:21], 0, 16
	s_waitcnt vmcnt(18)
; __device__ __forceinline__ void wcomb_item(const float* w_in, const float* wg, const float* ngain, bf16_t* WinT, int item, int lane) {
;     ...
; #pragma unroll 4
;     for (int cin = 0; cin < 128; ++cin) { const float av = ap[cin]; const f32x4 b0 = *(const f32x4*)(bp + (size_t)cin * 128), b1 = *(const f32x4*)(bp + (size_t)cin * 128 + 4); c0 += b0 * av; c1 += b1 * av; }
	v_pk_fma_f32 v[12:13], v[184:185], v[180:181], v[12:13] op_sel_hi:[1,0,1]
	v_pk_fma_f32 v[8:9], v[186:187], v[180:181], v[8:9] op_sel_hi:[1,0,1]
	v_pk_fma_f32 v[14:15], v[188:189], v[180:181], v[14:15] op_sel_hi:[1,0,1]
	v_pk_fma_f32 v[10:11], v[190:191], v[180:181], v[10:11] op_sel_hi:[1,0,1]
	v_pk_fma_f32 v[12:13], v[192:193], v[180:181], v[12:13] op_sel:[0,1,0]
	v_pk_fma_f32 v[8:9], v[194:195], v[180:181], v[8:9] op_sel:[0,1,0]
	v_pk_fma_f32 v[14:15], v[196:197], v[180:181], v[14:15] op_sel:[0,1,0]
	v_pk_fma_f32 v[10:11], v[198:199], v[180:181], v[10:11] op_sel:[0,1,0]
	v_pk_fma_f32 v[12:13], v[200:201], v[182:183], v[12:13] op_sel_hi:[1,0,1]
	v_pk_fma_f32 v[8:9], v[202:203], v[182:183], v[8:9] op_sel_hi:[1,0,1]
	v_pk_fma_f32 v[14:15], v[204:205], v[182:183], v[14:15] op_sel_hi:[1,0,1]
	v_pk_fma_f32 v[10:11], v[206:207], v[182:183], v[10:11] op_sel_hi:[1,0,1]
	v_pk_fma_f32 v[12:13], v[208:209], v[182:183], v[12:13] op_sel:[0,1,0]
	v_pk_fma_f32 v[8:9], v[210:211], v[182:183], v[8:9] op_sel:[0,1,0]
	v_pk_fma_f32 v[14:15], v[212:213], v[182:183], v[14:15] op_sel:[0,1,0]
	v_pk_fma_f32 v[10:11], v[214:215], v[182:183], v[10:11] op_sel:[0,1,0]
	global_load_dwordx4 v[180:183], v[20:21], off offset:-8
	v_lshl_add_u64 v[116:117], v[18:19], 0, s[6:7]
	global_load_dwordx4 v[184:187], v[116:117], off
	global_load_dwordx4 v[188:191], v[116:117], off offset:16
	global_load_dwordx4 v[192:195], v[116:117], off offset:512
	global_load_dwordx4 v[196:199], v[116:117], off offset:528
	global_load_dwordx4 v[200:203], v[116:117], off offset:1024
	global_load_dwordx4 v[204:207], v[116:117], off offset:1040
	global_load_dwordx4 v[208:211], v[116:117], off offset:1536
	global_load_dwordx4 v[212:215], v[116:117], off offset:1552
	s_add_u32 s6, s6, 0x800
	s_addc_u32 s7, s7, 0
	v_lshl_add_u64 v[20:21], v[20:21], 0, 16
	s_waitcnt vmcnt(18)
	v_pk_fma_f32 v[12:13], v[84:85], v[80:81], v[12:13] op_sel_hi:[1,0,1]
	v_pk_fma_f32 v[8:9], v[86:87], v[80:81], v[8:9] op_sel_hi:[1,0,1]
	v_pk_fma_f32 v[14:15], v[88:89], v[80:81], v[14:15] op_sel_hi:[1,0,1]
	v_pk_fma_f32 v[10:11], v[90:91], v[80:81], v[10:11] op_sel_hi:[1,0,1]
	v_pk_fma_f32 v[12:13], v[92:93], v[80:81], v[12:13] op_sel:[0,1,0]
	v_pk_fma_f32 v[8:9], v[94:95], v[80:81], v[8:9] op_sel:[0,1,0]
	v_pk_fma_f32 v[14:15], v[96:97], v[80:81], v[14:15] op_sel:[0,1,0]
	v_pk_fma_f32 v[10:11], v[98:99], v[80:81], v[10:11] op_sel:[0,1,0]
	v_pk_fma_f32 v[12:13], v[100:101], v[82:83], v[12:13] op_sel_hi:[1,0,1]
	v_pk_fma_f32 v[8:9], v[102:103], v[82:83], v[8:9] op_sel_hi:[1,0,1]
	v_pk_fma_f32 v[14:15], v[104:105], v[82:83], v[14:15] op_sel_hi:[1,0,1]
	v_pk_fma_f32 v[10:11], v[106:107], v[82:83], v[10:11] op_sel_hi:[1,0,1]
	v_pk_fma_f32 v[12:13], v[108:109], v[82:83], v[12:13] op_sel:[0,1,0]
	v_pk_fma_f32 v[8:9], v[110:111], v[82:83], v[8:9] op_sel:[0,1,0]
	v_pk_fma_f32 v[14:15], v[112:113], v[82:83], v[14:15] op_sel:[0,1,0]
	v_pk_fma_f32 v[10:11], v[114:115], v[82:83], v[10:11] op_sel:[0,1,0]
	global_load_dwordx4 v[80:83], v[20:21], off offset:-8
	v_lshl_add_u64 v[116:117], v[18:19], 0, s[6:7]
	global_load_dwordx4 v[84:87], v[116:117], off
	global_load_dwordx4 v[88:91], v[116:117], off offset:16
	global_load_dwordx4 v[92:95], v[116:117], off offset:512
	global_load_dwordx4 v[96:99], v[116:117], off offset:528
	global_load_dwordx4 v[100:103], v[116:117], off offset:1024
	global_load_dwordx4 v[104:107], v[116:117], off offset:1040
	global_load_dwordx4 v[108:111], v[116:117], off offset:1536
	global_load_dwordx4 v[112:115], v[116:117], off offset:1552
	s_add_u32 s6, s6, 0x800
	s_addc_u32 s7, s7, 0
	v_lshl_add_u64 v[20:21], v[20:21], 0, 16
	s_waitcnt vmcnt(18)
	v_pk_fma_f32 v[12:13], v[148:149], v[144:145], v[12:13] op_sel_hi:[1,0,1]
	v_pk_fma_f32 v[8:9], v[150:151], v[144:145], v[8:9] op_sel_hi:[1,0,1]
	v_pk_fma_f32 v[14:15], v[152:153], v[144:145], v[14:15] op_sel_hi:[1,0,1]
	v_pk_fma_f32 v[10:11], v[154:155], v[144:145], v[10:11] op_sel_hi:[1,0,1]
	v_pk_fma_f32 v[12:13], v[156:157], v[144:145], v[12:13] op_sel:[0,1,0]
	v_pk_fma_f32 v[8:9], v[158:159], v[144:145], v[8:9] op_sel:[0,1,0]
	v_pk_fma_f32 v[14:15], v[160:161], v[144:145], v[14:15] op_sel:[0,1,0]
	v_pk_fma_f32 v[10:11], v[162:163], v[144:145], v[10:11] op_sel:[0,1,0]
	v_pk_fma_f32 v[12:13], v[164:165], v[146:147], v[12:13] op_sel_hi:[1,0,1]
	v_pk_fma_f32 v[8:9], v[166:167], v[146:147], v[8:9] op_sel_hi:[1,0,1]
	v_pk_fma_f32 v[14:15], v[168:169], v[146:147], v[14:15] op_sel_hi:[1,0,1]
	v_pk_fma_f32 v[10:11], v[170:171], v[146:147], v[10:11] op_sel_hi:[1,0,1]
	v_pk_fma_f32 v[12:13], v[172:173], v[146:147], v[12:13] op_sel:[0,1,0]
	v_pk_fma_f32 v[8:9], v[174:175], v[146:147], v[8:9] op_sel:[0,1,0]
	v_pk_fma_f32 v[14:15], v[176:177], v[146:147], v[14:15] op_sel:[0,1,0]
	v_pk_fma_f32 v[10:11], v[178:179], v[146:147], v[10:11] op_sel:[0,1,0]
	global_load_dwordx4 v[144:147], v[20:21], off offset:-8
	v_lshl_add_u64 v[116:117], v[18:19], 0, s[6:7]
	global_load_dwordx4 v[148:151], v[116:117], off
	global_load_dwordx4 v[152:155], v[116:117], off offset:16
	global_load_dwordx4 v[156:159], v[116:117], off offset:512
	global_load_dwordx4 v[160:163], v[116:117], off offset:528
	global_load_dwordx4 v[164:167], v[116:117], off offset:1024
	global_load_dwordx4 v[168:171], v[116:117], off offset:1040
	global_load_dwordx4 v[172:175], v[116:117], off offset:1536
	global_load_dwordx4 v[176:179], v[116:117], off offset:1552
	s_add_u32 s6, s6, 0x800
	s_addc_u32 s7, s7, 0
	v_lshl_add_u64 v[20:21], v[20:21], 0, 16
	s_waitcnt vmcnt(18)
; __device__ __forceinline__ void wcomb_item(const float* w_in, const float* wg, const float* ngain, bf16_t* WinT, int item, int lane) {
;     ...
; #pragma unroll 4
;     for (int cin = 0; cin < 128; ++cin) { const float av = ap[cin]; const f32x4 b0 = *(const f32x4*)(bp + (size_t)cin * 128), b1 = *(const f32x4*)(bp + (size_t)cin * 128 + 4); c0 += b0 * av; c1 += b1 * av; }
	v_pk_fma_f32 v[12:13], v[184:185], v[180:181], v[12:13] op_sel_hi:[1,0,1]
	v_pk_fma_f32 v[8:9], v[186:187], v[180:181], v[8:9] op_sel_hi:[1,0,1]
	v_pk_fma_f32 v[14:15], v[188:189], v[180:181], v[14:15] op_sel_hi:[1,0,1]
	v_pk_fma_f32 v[10:11], v[190:191], v[180:181], v[10:11] op_sel_hi:[1,0,1]
	v_pk_fma_f32 v[12:13], v[192:193], v[180:181], v[12:13] op_sel:[0,1,0]
	v_pk_fma_f32 v[8:9], v[194:195], v[180:181], v[8:9] op_sel:[0,1,0]
	v_pk_fma_f32 v[14:15], v[196:197], v[180:181], v[14:15] op_sel:[0,1,0]
	v_pk_fma_f32 v[10:11], v[198:199], v[180:181], v[10:11] op_sel:[0,1,0]
	v_pk_fma_f32 v[12:13], v[200:201], v[182:183], v[12:13] op_sel_hi:[1,0,1]
	v_pk_fma_f32 v[8:9], v[202:203], v[182:183], v[8:9] op_sel_hi:[1,0,1]
	v_pk_fma_f32 v[14:15], v[204:205], v[182:183], v[14:15] op_sel_hi:[1,0,1]
	v_pk_fma_f32 v[10:11], v[206:207], v[182:183], v[10:11] op_sel_hi:[1,0,1]
	v_pk_fma_f32 v[12:13], v[208:209], v[182:183], v[12:13] op_sel:[0,1,0]
	v_pk_fma_f32 v[8:9], v[210:211], v[182:183], v[8:9] op_sel:[0,1,0]
	v_pk_fma_f32 v[14:15], v[212:213], v[182:183], v[14:15] op_sel:[0,1,0]
	v_pk_fma_f32 v[10:11], v[214:215], v[182:183], v[10:11] op_sel:[0,1,0]
	global_load_dwordx4 v[180:183], v[20:21], off offset:-8
	v_lshl_add_u64 v[116:117], v[18:19], 0, s[6:7]
	global_load_dwordx4 v[184:187], v[116:117], off
	global_load_dwordx4 v[188:191], v[116:117], off offset:16
	global_load_dwordx4 v[192:195], v[116:117], off offset:512
	global_load_dwordx4 v[196:199], v[116:117], off offset:528
	global_load_dwordx4 v[200:203], v[116:117], off offset:1024
	global_load_dwordx4 v[204:207], v[116:117], off offset:1040
	global_load_dwordx4 v[208:211], v[116:117], off offset:1536
	global_load_dwordx4 v[212:215], v[116:117], off offset:1552
	s_add_u32 s6, s6, 0x800
	s_addc_u32 s7, s7, 0
	v_lshl_add_u64 v[20:21], v[20:21], 0, 16
	s_waitcnt vmcnt(18)
	v_pk_fma_f32 v[12:13], v[84:85], v[80:81], v[12:13] op_sel_hi:[1,0,1]
	v_pk_fma_f32 v[8:9], v[86:87], v[80:81], v[8:9] op_sel_hi:[1,0,1]
	v_pk_fma_f32 v[14:15], v[88:89], v[80:81], v[14:15] op_sel_hi:[1,0,1]
	v_pk_fma_f32 v[10:11], v[90:91], v[80:81], v[10:11] op_sel_hi:[1,0,1]
	v_pk_fma_f32 v[12:13], v[92:93], v[80:81], v[12:13] op_sel:[0,1,0]
	v_pk_fma_f32 v[8:9], v[94:95], v[80:81], v[8:9] op_sel:[0,1,0]
	v_pk_fma_f32 v[14:15], v[96:97], v[80:81], v[14:15] op_sel:[0,1,0]
	v_pk_fma_f32 v[10:11], v[98:99], v[80:81], v[10:11] op_sel:[0,1,0]
	v_pk_fma_f32 v[12:13], v[100:101], v[82:83], v[12:13] op_sel_hi:[1,0,1]
	v_pk_fma_f32 v[8:9], v[102:103], v[82:83], v[8:9] op_sel_hi:[1,0,1]
	v_pk_fma_f32 v[14:15], v[104:105], v[82:83], v[14:15] op_sel_hi:[1,0,1]
	v_pk_fma_f32 v[10:11], v[106:107], v[82:83], v[10:11] op_sel_hi:[1,0,1]
	v_pk_fma_f32 v[12:13], v[108:109], v[82:83], v[12:13] op_sel:[0,1,0]
	v_pk_fma_f32 v[8:9], v[110:111], v[82:83], v[8:9] op_sel:[0,1,0]
	v_pk_fma_f32 v[14:15], v[112:113], v[82:83], v[14:15] op_sel:[0,1,0]
	v_pk_fma_f32 v[10:11], v[114:115], v[82:83], v[10:11] op_sel:[0,1,0]
	global_load_dwordx4 v[80:83], v[20:21], off offset:-8
	v_lshl_add_u64 v[116:117], v[18:19], 0, s[6:7]
	global_load_dwordx4 v[84:87], v[116:117], off
	global_load_dwordx4 v[88:91], v[116:117], off offset:16
	global_load_dwordx4 v[92:95], v[116:117], off offset:512
	global_load_dwordx4 v[96:99], v[116:117], off offset:528
	global_load_dwordx4 v[100:103], v[116:117], off offset:1024
	global_load_dwordx4 v[104:107], v[116:117], off offset:1040
	global_load_dwordx4 v[108:111], v[116:117], off offset:1536
	global_load_dwordx4 v[112:115], v[116:117], off offset:1552
	s_add_u32 s6, s6, 0x800
	s_addc_u32 s7, s7, 0
	v_lshl_add_u64 v[20:21], v[20:21], 0, 16
	s_waitcnt vmcnt(18)
	v_pk_fma_f32 v[12:13], v[148:149], v[144:145], v[12:13] op_sel_hi:[1,0,1]
	v_pk_fma_f32 v[8:9], v[150:151], v[144:145], v[8:9] op_sel_hi:[1,0,1]
	v_pk_fma_f32 v[14:15], v[152:153], v[144:145], v[14:15] op_sel_hi:[1,0,1]
	v_pk_fma_f32 v[10:11], v[154:155], v[144:145], v[10:11] op_sel_hi:[1,0,1]
	v_pk_fma_f32 v[12:13], v[156:157], v[144:145], v[12:13] op_sel:[0,1,0]
	v_pk_fma_f32 v[8:9], v[158:159], v[144:145], v[8:9] op_sel:[0,1,0]
	v_pk_fma_f32 v[14:15], v[160:161], v[144:145], v[14:15] op_sel:[0,1,0]
	v_pk_fma_f32 v[10:11], v[162:163], v[144:145], v[10:11] op_sel:[0,1,0]
	v_pk_fma_f32 v[12:13], v[164:165], v[146:147], v[12:13] op_sel_hi:[1,0,1]
	v_pk_fma_f32 v[8:9], v[166:167], v[146:147], v[8:9] op_sel_hi:[1,0,1]
	v_pk_fma_f32 v[14:15], v[168:169], v[146:147], v[14:15] op_sel_hi:[1,0,1]
	v_pk_fma_f32 v[10:11], v[170:171], v[146:147], v[10:11] op_sel_hi:[1,0,1]
	v_pk_fma_f32 v[12:13], v[172:173], v[146:147], v[12:13] op_sel:[0,1,0]
	v_pk_fma_f32 v[8:9], v[174:175], v[146:147], v[8:9] op_sel:[0,1,0]
	v_pk_fma_f32 v[14:15], v[176:177], v[146:147], v[14:15] op_sel:[0,1,0]
	v_pk_fma_f32 v[10:11], v[178:179], v[146:147], v[10:11] op_sel:[0,1,0]
	global_load_dwordx4 v[144:147], v[20:21], off offset:-8
	v_lshl_add_u64 v[116:117], v[18:19], 0, s[6:7]
	global_load_dwordx4 v[148:151], v[116:117], off
	global_load_dwordx4 v[152:155], v[116:117], off offset:16
	global_load_dwordx4 v[156:159], v[116:117], off offset:512
	global_load_dwordx4 v[160:163], v[116:117], off offset:528
	global_load_dwordx4 v[164:167], v[116:117], off offset:1024
	global_load_dwordx4 v[168:171], v[116:117], off offset:1040
	global_load_dwordx4 v[172:175], v[116:117], off offset:1536
	global_load_dwordx4 v[176:179], v[116:117], off offset:1552
	s_add_u32 s6, s6, 0x800
	s_addc_u32 s7, s7, 0
	v_lshl_add_u64 v[20:21], v[20:21], 0, 16
	s_waitcnt vmcnt(18)
; __device__ __forceinline__ void wcomb_item(const float* w_in, const float* wg, const float* ngain, bf16_t* WinT, int item, int lane) {
;     ...
;     const float* ap = w_in + (size_t)k * DIN + 128 * g; const float* bp = wg + (size_t)g * 128 * 128 + d0;
;     f32x4 c0 = (f32x4){0.f, 0.f, 0.f, 0.f}, c1 = c0;
; #pragma unroll 4
;     for (int cin = 0; cin < 128; ++cin) { const float av = ap[cin]; const f32x4 b0 = *(const f32x4*)(bp + (size_t)cin * 128), b1 = *(const f32x4*)(bp + (size_t)cin * 128 + 4); c0 += b0 * av; c1 += b1 * av; }
	v_pk_fma_f32 v[12:13], v[184:185], v[180:181], v[12:13] op_sel_hi:[1,0,1]
	v_pk_fma_f32 v[8:9], v[186:187], v[180:181], v[8:9] op_sel_hi:[1,0,1]
	v_pk_fma_f32 v[14:15], v[188:189], v[180:181], v[14:15] op_sel_hi:[1,0,1]
	v_pk_fma_f32 v[10:11], v[190:191], v[180:181], v[10:11] op_sel_hi:[1,0,1]
	v_pk_fma_f32 v[12:13], v[192:193], v[180:181], v[12:13] op_sel:[0,1,0]
	v_pk_fma_f32 v[8:9], v[194:195], v[180:181], v[8:9] op_sel:[0,1,0]
	v_pk_fma_f32 v[14:15], v[196:197], v[180:181], v[14:15] op_sel:[0,1,0]
	v_pk_fma_f32 v[10:11], v[198:199], v[180:181], v[10:11] op_sel:[0,1,0]
	v_pk_fma_f32 v[12:13], v[200:201], v[182:183], v[12:13] op_sel_hi:[1,0,1]
	v_pk_fma_f32 v[8:9], v[202:203], v[182:183], v[8:9] op_sel_hi:[1,0,1]
	v_pk_fma_f32 v[14:15], v[204:205], v[182:183], v[14:15] op_sel_hi:[1,0,1]
	v_pk_fma_f32 v[10:11], v[206:207], v[182:183], v[10:11] op_sel_hi:[1,0,1]
	v_pk_fma_f32 v[12:13], v[208:209], v[182:183], v[12:13] op_sel:[0,1,0]
	v_pk_fma_f32 v[8:9], v[210:211], v[182:183], v[8:9] op_sel:[0,1,0]
	v_pk_fma_f32 v[14:15], v[212:213], v[182:183], v[14:15] op_sel:[0,1,0]
	v_pk_fma_f32 v[10:11], v[214:215], v[182:183], v[10:11] op_sel:[0,1,0]
	global_load_dwordx4 v[180:183], v[20:21], off offset:-8
	v_lshl_add_u64 v[116:117], v[18:19], 0, s[6:7]
	global_load_dwordx4 v[184:187], v[116:117], off
	global_load_dwordx4 v[188:191], v[116:117], off offset:16
	global_load_dwordx4 v[192:195], v[116:117], off offset:512
	global_load_dwordx4 v[196:199], v[116:117], off offset:528
	global_load_dwordx4 v[200:203], v[116:117], off offset:1024
	global_load_dwordx4 v[204:207], v[116:117], off offset:1040
	global_load_dwordx4 v[208:211], v[116:117], off offset:1536
	global_load_dwordx4 v[212:215], v[116:117], off offset:1552
	s_add_u32 s6, s6, 0x800
	s_addc_u32 s7, s7, 0
	v_lshl_add_u64 v[20:21], v[20:21], 0, 16
	s_waitcnt vmcnt(18)
	v_pk_fma_f32 v[12:13], v[84:85], v[80:81], v[12:13] op_sel_hi:[1,0,1]
	v_pk_fma_f32 v[8:9], v[86:87], v[80:81], v[8:9] op_sel_hi:[1,0,1]
	v_pk_fma_f32 v[14:15], v[88:89], v[80:81], v[14:15] op_sel_hi:[1,0,1]
	v_pk_fma_f32 v[10:11], v[90:91], v[80:81], v[10:11] op_sel_hi:[1,0,1]
	v_pk_fma_f32 v[12:13], v[92:93], v[80:81], v[12:13] op_sel:[0,1,0]
	v_pk_fma_f32 v[8:9], v[94:95], v[80:81], v[8:9] op_sel:[0,1,0]
	v_pk_fma_f32 v[14:15], v[96:97], v[80:81], v[14:15] op_sel:[0,1,0]
	v_pk_fma_f32 v[10:11], v[98:99], v[80:81], v[10:11] op_sel:[0,1,0]
	v_pk_fma_f32 v[12:13], v[100:101], v[82:83], v[12:13] op_sel_hi:[1,0,1]
	v_pk_fma_f32 v[8:9], v[102:103], v[82:83], v[8:9] op_sel_hi:[1,0,1]
	v_pk_fma_f32 v[14:15], v[104:105], v[82:83], v[14:15] op_sel_hi:[1,0,1]
	v_pk_fma_f32 v[10:11], v[106:107], v[82:83], v[10:11] op_sel_hi:[1,0,1]
	v_pk_fma_f32 v[12:13], v[108:109], v[82:83], v[12:13] op_sel:[0,1,0]
	v_pk_fma_f32 v[8:9], v[110:111], v[82:83], v[8:9] op_sel:[0,1,0]
	v_pk_fma_f32 v[14:15], v[112:113], v[82:83], v[14:15] op_sel:[0,1,0]
	v_pk_fma_f32 v[10:11], v[114:115], v[82:83], v[10:11] op_sel:[0,1,0]
	global_load_dwordx4 v[80:83], v[20:21], off offset:-8
	v_lshl_add_u64 v[116:117], v[18:19], 0, s[6:7]
	global_load_dwordx4 v[84:87], v[116:117], off
	global_load_dwordx4 v[88:91], v[116:117], off offset:16
	global_load_dwordx4 v[92:95], v[116:117], off offset:512
	global_load_dwordx4 v[96:99], v[116:117], off offset:528
	global_load_dwordx4 v[100:103], v[116:117], off offset:1024
	global_load_dwordx4 v[104:107], v[116:117], off offset:1040
	global_load_dwordx4 v[108:111], v[116:117], off offset:1536
	global_load_dwordx4 v[112:115], v[116:117], off offset:1552
	s_add_u32 s6, s6, 0x800
	s_addc_u32 s7, s7, 0
	v_lshl_add_u64 v[20:21], v[20:21], 0, 16
	s_waitcnt vmcnt(18)
	v_pk_fma_f32 v[12:13], v[148:149], v[144:145], v[12:13] op_sel_hi:[1,0,1]
	v_pk_fma_f32 v[8:9], v[150:151], v[144:145], v[8:9] op_sel_hi:[1,0,1]
	v_pk_fma_f32 v[14:15], v[152:153], v[144:145], v[14:15] op_sel_hi:[1,0,1]
	v_pk_fma_f32 v[10:11], v[154:155], v[144:145], v[10:11] op_sel_hi:[1,0,1]
	v_pk_fma_f32 v[12:13], v[156:157], v[144:145], v[12:13] op_sel:[0,1,0]
	v_pk_fma_f32 v[8:9], v[158:159], v[144:145], v[8:9] op_sel:[0,1,0]
	v_pk_fma_f32 v[14:15], v[160:161], v[144:145], v[14:15] op_sel:[0,1,0]
	v_pk_fma_f32 v[10:11], v[162:163], v[144:145], v[10:11] op_sel:[0,1,0]
	v_pk_fma_f32 v[12:13], v[164:165], v[146:147], v[12:13] op_sel_hi:[1,0,1]
	v_pk_fma_f32 v[8:9], v[166:167], v[146:147], v[8:9] op_sel_hi:[1,0,1]
	v_pk_fma_f32 v[14:15], v[168:169], v[146:147], v[14:15] op_sel_hi:[1,0,1]
	v_pk_fma_f32 v[10:11], v[170:171], v[146:147], v[10:11] op_sel_hi:[1,0,1]
	v_pk_fma_f32 v[12:13], v[172:173], v[146:147], v[12:13] op_sel:[0,1,0]
	v_pk_fma_f32 v[8:9], v[174:175], v[146:147], v[8:9] op_sel:[0,1,0]
	v_pk_fma_f32 v[14:15], v[176:177], v[146:147], v[14:15] op_sel:[0,1,0]
	v_pk_fma_f32 v[10:11], v[178:179], v[146:147], v[10:11] op_sel:[0,1,0]
	global_load_dwordx4 v[144:147], v[20:21], off offset:-8
	v_lshl_add_u64 v[116:117], v[18:19], 0, s[6:7]
	global_load_dwordx4 v[148:151], v[116:117], off
	global_load_dwordx4 v[152:155], v[116:117], off offset:16
	global_load_dwordx4 v[156:159], v[116:117], off offset:512
	global_load_dwordx4 v[160:163], v[116:117], off offset:528
	global_load_dwordx4 v[164:167], v[116:117], off offset:1024
	global_load_dwordx4 v[168:171], v[116:117], off offset:1040
	global_load_dwordx4 v[172:175], v[116:117], off offset:1536
	global_load_dwordx4 v[176:179], v[116:117], off offset:1552
	s_add_u32 s6, s6, 0x800
	s_addc_u32 s7, s7, 0
	v_lshl_add_u64 v[20:21], v[20:21], 0, 16
	s_waitcnt vmcnt(18)
; __device__ __forceinline__ void wcomb_item(const float* w_in, const float* wg, const float* ngain, bf16_t* WinT, int item, int lane) {
;     ...
;     const float* ap = w_in + (size_t)k * DIN + 128 * g; const float* bp = wg + (size_t)g * 128 * 128 + d0;
;     f32x4 c0 = (f32x4){0.f, 0.f, 0.f, 0.f}, c1 = c0;
; #pragma unroll 4
;     for (int cin = 0; cin < 128; ++cin) { const float av = ap[cin]; const f32x4 b0 = *(const f32x4*)(bp + (size_t)cin * 128), b1 = *(const f32x4*)(bp + (size_t)cin * 128 + 4); c0 += b0 * av; c1 += b1 * av; }
	v_pk_fma_f32 v[12:13], v[184:185], v[180:181], v[12:13] op_sel_hi:[1,0,1]
	v_pk_fma_f32 v[8:9], v[186:187], v[180:181], v[8:9] op_sel_hi:[1,0,1]
	v_pk_fma_f32 v[14:15], v[188:189], v[180:181], v[14:15] op_sel_hi:[1,0,1]
	v_pk_fma_f32 v[10:11], v[190:191], v[180:181], v[10:11] op_sel_hi:[1,0,1]
	v_pk_fma_f32 v[12:13], v[192:193], v[180:181], v[12:13] op_sel:[0,1,0]
	v_pk_fma_f32 v[8:9], v[194:195], v[180:181], v[8:9] op_sel:[0,1,0]
	v_pk_fma_f32 v[14:15], v[196:197], v[180:181], v[14:15] op_sel:[0,1,0]
	v_pk_fma_f32 v[10:11], v[198:199], v[180:181], v[10:11] op_sel:[0,1,0]
	v_pk_fma_f32 v[12:13], v[200:201], v[182:183], v[12:13] op_sel_hi:[1,0,1]
	v_pk_fma_f32 v[8:9], v[202:203], v[182:183], v[8:9] op_sel_hi:[1,0,1]
	v_pk_fma_f32 v[14:15], v[204:205], v[182:183], v[14:15] op_sel_hi:[1,0,1]
	v_pk_fma_f32 v[10:11], v[206:207], v[182:183], v[10:11] op_sel_hi:[1,0,1]
	v_pk_fma_f32 v[12:13], v[208:209], v[182:183], v[12:13] op_sel:[0,1,0]
	v_pk_fma_f32 v[8:9], v[210:211], v[182:183], v[8:9] op_sel:[0,1,0]
	v_pk_fma_f32 v[14:15], v[212:213], v[182:183], v[14:15] op_sel:[0,1,0]
	v_pk_fma_f32 v[10:11], v[214:215], v[182:183], v[10:11] op_sel:[0,1,0]
	global_load_dwordx4 v[180:183], v[20:21], off offset:-8
	v_lshl_add_u64 v[116:117], v[18:19], 0, s[6:7]
	global_load_dwordx4 v[184:187], v[116:117], off
	global_load_dwordx4 v[188:191], v[116:117], off offset:16
	global_load_dwordx4 v[192:195], v[116:117], off offset:512
	global_load_dwordx4 v[196:199], v[116:117], off offset:528
	global_load_dwordx4 v[200:203], v[116:117], off offset:1024
	global_load_dwordx4 v[204:207], v[116:117], off offset:1040
	global_load_dwordx4 v[208:211], v[116:117], off offset:1536
	global_load_dwordx4 v[212:215], v[116:117], off offset:1552
	s_add_u32 s6, s6, 0x800
	s_addc_u32 s7, s7, 0
	v_lshl_add_u64 v[20:21], v[20:21], 0, 16
	s_waitcnt vmcnt(18)
	v_pk_fma_f32 v[12:13], v[84:85], v[80:81], v[12:13] op_sel_hi:[1,0,1]
	v_pk_fma_f32 v[8:9], v[86:87], v[80:81], v[8:9] op_sel_hi:[1,0,1]
	v_pk_fma_f32 v[14:15], v[88:89], v[80:81], v[14:15] op_sel_hi:[1,0,1]
	v_pk_fma_f32 v[10:11], v[90:91], v[80:81], v[10:11] op_sel_hi:[1,0,1]
	v_pk_fma_f32 v[12:13], v[92:93], v[80:81], v[12:13] op_sel:[0,1,0]
	v_pk_fma_f32 v[8:9], v[94:95], v[80:81], v[8:9] op_sel:[0,1,0]
	v_pk_fma_f32 v[14:15], v[96:97], v[80:81], v[14:15] op_sel:[0,1,0]
	v_pk_fma_f32 v[10:11], v[98:99], v[80:81], v[10:11] op_sel:[0,1,0]
	v_pk_fma_f32 v[12:13], v[100:101], v[82:83], v[12:13] op_sel_hi:[1,0,1]
	v_pk_fma_f32 v[8:9], v[102:103], v[82:83], v[8:9] op_sel_hi:[1,0,1]
	v_pk_fma_f32 v[14:15], v[104:105], v[82:83], v[14:15] op_sel_hi:[1,0,1]
	v_pk_fma_f32 v[10:11], v[106:107], v[82:83], v[10:11] op_sel_hi:[1,0,1]
	v_pk_fma_f32 v[12:13], v[108:109], v[82:83], v[12:13] op_sel:[0,1,0]
	v_pk_fma_f32 v[8:9], v[110:111], v[82:83], v[8:9] op_sel:[0,1,0]
	v_pk_fma_f32 v[14:15], v[112:113], v[82:83], v[14:15] op_sel:[0,1,0]
	v_pk_fma_f32 v[10:11], v[114:115], v[82:83], v[10:11] op_sel:[0,1,0]
	global_load_dwordx4 v[80:83], v[20:21], off offset:-8
	v_lshl_add_u64 v[116:117], v[18:19], 0, s[6:7]
	global_load_dwordx4 v[84:87], v[116:117], off
	global_load_dwordx4 v[88:91], v[116:117], off offset:16
	global_load_dwordx4 v[92:95], v[116:117], off offset:512
	global_load_dwordx4 v[96:99], v[116:117], off offset:528
	global_load_dwordx4 v[100:103], v[116:117], off offset:1024
	global_load_dwordx4 v[104:107], v[116:117], off offset:1040
	global_load_dwordx4 v[108:111], v[116:117], off offset:1536
	global_load_dwordx4 v[112:115], v[116:117], off offset:1552
	s_add_u32 s6, s6, 0x800
	s_addc_u32 s7, s7, 0
	v_lshl_add_u64 v[20:21], v[20:21], 0, 16
	s_waitcnt vmcnt(18)
	v_pk_fma_f32 v[12:13], v[148:149], v[144:145], v[12:13] op_sel_hi:[1,0,1]
	v_pk_fma_f32 v[8:9], v[150:151], v[144:145], v[8:9] op_sel_hi:[1,0,1]
	v_pk_fma_f32 v[14:15], v[152:153], v[144:145], v[14:15] op_sel_hi:[1,0,1]
	v_pk_fma_f32 v[10:11], v[154:155], v[144:145], v[10:11] op_sel_hi:[1,0,1]
	v_pk_fma_f32 v[12:13], v[156:157], v[144:145], v[12:13] op_sel:[0,1,0]
	v_pk_fma_f32 v[8:9], v[158:159], v[144:145], v[8:9] op_sel:[0,1,0]
	v_pk_fma_f32 v[14:15], v[160:161], v[144:145], v[14:15] op_sel:[0,1,0]
	v_pk_fma_f32 v[10:11], v[162:163], v[144:145], v[10:11] op_sel:[0,1,0]
	v_pk_fma_f32 v[12:13], v[164:165], v[146:147], v[12:13] op_sel_hi:[1,0,1]
	v_pk_fma_f32 v[8:9], v[166:167], v[146:147], v[8:9] op_sel_hi:[1,0,1]
	v_pk_fma_f32 v[14:15], v[168:169], v[146:147], v[14:15] op_sel_hi:[1,0,1]
	v_pk_fma_f32 v[10:11], v[170:171], v[146:147], v[10:11] op_sel_hi:[1,0,1]
	v_pk_fma_f32 v[12:13], v[172:173], v[146:147], v[12:13] op_sel:[0,1,0]
	v_pk_fma_f32 v[8:9], v[174:175], v[146:147], v[8:9] op_sel:[0,1,0]
	v_pk_fma_f32 v[14:15], v[176:177], v[146:147], v[14:15] op_sel:[0,1,0]
	v_pk_fma_f32 v[10:11], v[178:179], v[146:147], v[10:11] op_sel:[0,1,0]
	global_load_dwordx4 v[144:147], v[20:21], off offset:-8
	v_lshl_add_u64 v[116:117], v[18:19], 0, s[6:7]
	global_load_dwordx4 v[148:151], v[116:117], off
	global_load_dwordx4 v[152:155], v[116:117], off offset:16
	global_load_dwordx4 v[156:159], v[116:117], off offset:512
	global_load_dwordx4 v[160:163], v[116:117], off offset:528
	global_load_dwordx4 v[164:167], v[116:117], off offset:1024
	global_load_dwordx4 v[168:171], v[116:117], off offset:1040
	global_load_dwordx4 v[172:175], v[116:117], off offset:1536
	global_load_dwordx4 v[176:179], v[116:117], off offset:1552
	s_add_u32 s6, s6, 0x800
	s_addc_u32 s7, s7, 0
	v_lshl_add_u64 v[20:21], v[20:21], 0, 16
	s_waitcnt vmcnt(18)
; __device__ __forceinline__ void wcomb_item(const float* w_in, const float* wg, const float* ngain, bf16_t* WinT, int item, int lane) {
;     ...
;     const float* ap = w_in + (size_t)k * DIN + 128 * g; const float* bp = wg + (size_t)g * 128 * 128 + d0;
;     f32x4 c0 = (f32x4){0.f, 0.f, 0.f, 0.f}, c1 = c0;
; #pragma unroll 4
;     for (int cin = 0; cin < 128; ++cin) { const float av = ap[cin]; const f32x4 b0 = *(const f32x4*)(bp + (size_t)cin * 128), b1 = *(const f32x4*)(bp + (size_t)cin * 128 + 4); c0 += b0 * av; c1 += b1 * av; }
	v_pk_fma_f32 v[12:13], v[184:185], v[180:181], v[12:13] op_sel_hi:[1,0,1]
	v_pk_fma_f32 v[8:9], v[186:187], v[180:181], v[8:9] op_sel_hi:[1,0,1]
	v_pk_fma_f32 v[14:15], v[188:189], v[180:181], v[14:15] op_sel_hi:[1,0,1]
	v_pk_fma_f32 v[10:11], v[190:191], v[180:181], v[10:11] op_sel_hi:[1,0,1]
	v_pk_fma_f32 v[12:13], v[192:193], v[180:181], v[12:13] op_sel:[0,1,0]
	v_pk_fma_f32 v[8:9], v[194:195], v[180:181], v[8:9] op_sel:[0,1,0]
	v_pk_fma_f32 v[14:15], v[196:197], v[180:181], v[14:15] op_sel:[0,1,0]
	v_pk_fma_f32 v[10:11], v[198:199], v[180:181], v[10:11] op_sel:[0,1,0]
	v_pk_fma_f32 v[12:13], v[200:201], v[182:183], v[12:13] op_sel_hi:[1,0,1]
	v_pk_fma_f32 v[8:9], v[202:203], v[182:183], v[8:9] op_sel_hi:[1,0,1]
	v_pk_fma_f32 v[14:15], v[204:205], v[182:183], v[14:15] op_sel_hi:[1,0,1]
	v_pk_fma_f32 v[10:11], v[206:207], v[182:183], v[10:11] op_sel_hi:[1,0,1]
	v_pk_fma_f32 v[12:13], v[208:209], v[182:183], v[12:13] op_sel:[0,1,0]
	v_pk_fma_f32 v[8:9], v[210:211], v[182:183], v[8:9] op_sel:[0,1,0]
	v_pk_fma_f32 v[14:15], v[212:213], v[182:183], v[14:15] op_sel:[0,1,0]
	v_pk_fma_f32 v[10:11], v[214:215], v[182:183], v[10:11] op_sel:[0,1,0]
	global_load_dwordx4 v[180:183], v[20:21], off offset:-8
	v_lshl_add_u64 v[116:117], v[18:19], 0, s[6:7]
	global_load_dwordx4 v[184:187], v[116:117], off
	global_load_dwordx4 v[188:191], v[116:117], off offset:16
	global_load_dwordx4 v[192:195], v[116:117], off offset:512
	global_load_dwordx4 v[196:199], v[116:117], off offset:528
	global_load_dwordx4 v[200:203], v[116:117], off offset:1024
	global_load_dwordx4 v[204:207], v[116:117], off offset:1040
	global_load_dwordx4 v[208:211], v[116:117], off offset:1536
	global_load_dwordx4 v[212:215], v[116:117], off offset:1552
	s_add_u32 s6, s6, 0x800
	s_addc_u32 s7, s7, 0
	v_lshl_add_u64 v[20:21], v[20:21], 0, 16
	s_waitcnt vmcnt(18)
	v_pk_fma_f32 v[12:13], v[84:85], v[80:81], v[12:13] op_sel_hi:[1,0,1]
	v_pk_fma_f32 v[8:9], v[86:87], v[80:81], v[8:9] op_sel_hi:[1,0,1]
	v_pk_fma_f32 v[14:15], v[88:89], v[80:81], v[14:15] op_sel_hi:[1,0,1]
	v_pk_fma_f32 v[10:11], v[90:91], v[80:81], v[10:11] op_sel_hi:[1,0,1]
	v_pk_fma_f32 v[12:13], v[92:93], v[80:81], v[12:13] op_sel:[0,1,0]
	v_pk_fma_f32 v[8:9], v[94:95], v[80:81], v[8:9] op_sel:[0,1,0]
	v_pk_fma_f32 v[14:15], v[96:97], v[80:81], v[14:15] op_sel:[0,1,0]
	v_pk_fma_f32 v[10:11], v[98:99], v[80:81], v[10:11] op_sel:[0,1,0]
	v_pk_fma_f32 v[12:13], v[100:101], v[82:83], v[12:13] op_sel_hi:[1,0,1]
	v_pk_fma_f32 v[8:9], v[102:103], v[82:83], v[8:9] op_sel_hi:[1,0,1]
	v_pk_fma_f32 v[14:15], v[104:105], v[82:83], v[14:15] op_sel_hi:[1,0,1]
	v_pk_fma_f32 v[10:11], v[106:107], v[82:83], v[10:11] op_sel_hi:[1,0,1]
	v_pk_fma_f32 v[12:13], v[108:109], v[82:83], v[12:13] op_sel:[0,1,0]
	v_pk_fma_f32 v[8:9], v[110:111], v[82:83], v[8:9] op_sel:[0,1,0]
	v_pk_fma_f32 v[14:15], v[112:113], v[82:83], v[14:15] op_sel:[0,1,0]
	v_pk_fma_f32 v[10:11], v[114:115], v[82:83], v[10:11] op_sel:[0,1,0]
	global_load_dwordx4 v[80:83], v[20:21], off offset:-8
	v_lshl_add_u64 v[116:117], v[18:19], 0, s[6:7]
	global_load_dwordx4 v[84:87], v[116:117], off
	global_load_dwordx4 v[88:91], v[116:117], off offset:16
	global_load_dwordx4 v[92:95], v[116:117], off offset:512
	global_load_dwordx4 v[96:99], v[116:117], off offset:528
	global_load_dwordx4 v[100:103], v[116:117], off offset:1024
	global_load_dwordx4 v[104:107], v[116:117], off offset:1040
	global_load_dwordx4 v[108:111], v[116:117], off offset:1536
	global_load_dwordx4 v[112:115], v[116:117], off offset:1552
	s_add_u32 s6, s6, 0x800
	s_addc_u32 s7, s7, 0
	v_lshl_add_u64 v[20:21], v[20:21], 0, 16
	s_waitcnt vmcnt(18)
	v_pk_fma_f32 v[12:13], v[148:149], v[144:145], v[12:13] op_sel_hi:[1,0,1]
	v_pk_fma_f32 v[8:9], v[150:151], v[144:145], v[8:9] op_sel_hi:[1,0,1]
	v_pk_fma_f32 v[14:15], v[152:153], v[144:145], v[14:15] op_sel_hi:[1,0,1]
	v_pk_fma_f32 v[10:11], v[154:155], v[144:145], v[10:11] op_sel_hi:[1,0,1]
	v_pk_fma_f32 v[12:13], v[156:157], v[144:145], v[12:13] op_sel:[0,1,0]
	v_pk_fma_f32 v[8:9], v[158:159], v[144:145], v[8:9] op_sel:[0,1,0]
	v_pk_fma_f32 v[14:15], v[160:161], v[144:145], v[14:15] op_sel:[0,1,0]
	v_pk_fma_f32 v[10:11], v[162:163], v[144:145], v[10:11] op_sel:[0,1,0]
	v_pk_fma_f32 v[12:13], v[164:165], v[146:147], v[12:13] op_sel_hi:[1,0,1]
	v_pk_fma_f32 v[8:9], v[166:167], v[146:147], v[8:9] op_sel_hi:[1,0,1]
	v_pk_fma_f32 v[14:15], v[168:169], v[146:147], v[14:15] op_sel_hi:[1,0,1]
	v_pk_fma_f32 v[10:11], v[170:171], v[146:147], v[10:11] op_sel_hi:[1,0,1]
	v_pk_fma_f32 v[12:13], v[172:173], v[146:147], v[12:13] op_sel:[0,1,0]
	v_pk_fma_f32 v[8:9], v[174:175], v[146:147], v[8:9] op_sel:[0,1,0]
	v_pk_fma_f32 v[14:15], v[176:177], v[146:147], v[14:15] op_sel:[0,1,0]
	v_pk_fma_f32 v[10:11], v[178:179], v[146:147], v[10:11] op_sel:[0,1,0]
	global_load_dwordx4 v[144:147], v[20:21], off offset:-8
	v_lshl_add_u64 v[116:117], v[18:19], 0, s[6:7]
	global_load_dwordx4 v[148:151], v[116:117], off
	global_load_dwordx4 v[152:155], v[116:117], off offset:16
	global_load_dwordx4 v[156:159], v[116:117], off offset:512
	global_load_dwordx4 v[160:163], v[116:117], off offset:528
	global_load_dwordx4 v[164:167], v[116:117], off offset:1024
	global_load_dwordx4 v[168:171], v[116:117], off offset:1040
	global_load_dwordx4 v[172:175], v[116:117], off offset:1536
	global_load_dwordx4 v[176:179], v[116:117], off offset:1552
	s_add_u32 s6, s6, 0x800
	s_addc_u32 s7, s7, 0
	v_lshl_add_u64 v[20:21], v[20:21], 0, 16
	s_waitcnt vmcnt(18)
; __device__ __forceinline__ void wcomb_item(const float* w_in, const float* wg, const float* ngain, bf16_t* WinT, int item, int lane) {
;     ...
;     const float* ap = w_in + (size_t)k * DIN + 128 * g; const float* bp = wg + (size_t)g * 128 * 128 + d0;
;     f32x4 c0 = (f32x4){0.f, 0.f, 0.f, 0.f}, c1 = c0;
; #pragma unroll 4
;     for (int cin = 0; cin < 128; ++cin) { const float av = ap[cin]; const f32x4 b0 = *(const f32x4*)(bp + (size_t)cin * 128), b1 = *(const f32x4*)(bp + (size_t)cin * 128 + 4); c0 += b0 * av; c1 += b1 * av; }
	v_pk_fma_f32 v[12:13], v[184:185], v[180:181], v[12:13] op_sel_hi:[1,0,1]
	v_pk_fma_f32 v[8:9], v[186:187], v[180:181], v[8:9] op_sel_hi:[1,0,1]
	v_pk_fma_f32 v[14:15], v[188:189], v[180:181], v[14:15] op_sel_hi:[1,0,1]
	v_pk_fma_f32 v[10:11], v[190:191], v[180:181], v[10:11] op_sel_hi:[1,0,1]
	v_pk_fma_f32 v[12:13], v[192:193], v[180:181], v[12:13] op_sel:[0,1,0]
	v_pk_fma_f32 v[8:9], v[194:195], v[180:181], v[8:9] op_sel:[0,1,0]
	v_pk_fma_f32 v[14:15], v[196:197], v[180:181], v[14:15] op_sel:[0,1,0]
	v_pk_fma_f32 v[10:11], v[198:199], v[180:181], v[10:11] op_sel:[0,1,0]
	v_pk_fma_f32 v[12:13], v[200:201], v[182:183], v[12:13] op_sel_hi:[1,0,1]
	v_pk_fma_f32 v[8:9], v[202:203], v[182:183], v[8:9] op_sel_hi:[1,0,1]
	v_pk_fma_f32 v[14:15], v[204:205], v[182:183], v[14:15] op_sel_hi:[1,0,1]
	v_pk_fma_f32 v[10:11], v[206:207], v[182:183], v[10:11] op_sel_hi:[1,0,1]
	v_pk_fma_f32 v[12:13], v[208:209], v[182:183], v[12:13] op_sel:[0,1,0]
	v_pk_fma_f32 v[8:9], v[210:211], v[182:183], v[8:9] op_sel:[0,1,0]
	v_pk_fma_f32 v[14:15], v[212:213], v[182:183], v[14:15] op_sel:[0,1,0]
	v_pk_fma_f32 v[10:11], v[214:215], v[182:183], v[10:11] op_sel:[0,1,0]
	global_load_dwordx4 v[180:183], v[20:21], off offset:-8
	v_lshl_add_u64 v[116:117], v[18:19], 0, s[6:7]
	global_load_dwordx4 v[184:187], v[116:117], off
	global_load_dwordx4 v[188:191], v[116:117], off offset:16
	global_load_dwordx4 v[192:195], v[116:117], off offset:512
	global_load_dwordx4 v[196:199], v[116:117], off offset:528
	global_load_dwordx4 v[200:203], v[116:117], off offset:1024
	global_load_dwordx4 v[204:207], v[116:117], off offset:1040
	global_load_dwordx4 v[208:211], v[116:117], off offset:1536
	global_load_dwordx4 v[212:215], v[116:117], off offset:1552
	s_add_u32 s6, s6, 0x800
	s_addc_u32 s7, s7, 0
	v_lshl_add_u64 v[20:21], v[20:21], 0, 16
	s_waitcnt vmcnt(18)
	v_pk_fma_f32 v[12:13], v[84:85], v[80:81], v[12:13] op_sel_hi:[1,0,1]
	v_pk_fma_f32 v[8:9], v[86:87], v[80:81], v[8:9] op_sel_hi:[1,0,1]
	v_pk_fma_f32 v[14:15], v[88:89], v[80:81], v[14:15] op_sel_hi:[1,0,1]
	v_pk_fma_f32 v[10:11], v[90:91], v[80:81], v[10:11] op_sel_hi:[1,0,1]
	v_pk_fma_f32 v[12:13], v[92:93], v[80:81], v[12:13] op_sel:[0,1,0]
	v_pk_fma_f32 v[8:9], v[94:95], v[80:81], v[8:9] op_sel:[0,1,0]
	v_pk_fma_f32 v[14:15], v[96:97], v[80:81], v[14:15] op_sel:[0,1,0]
	v_pk_fma_f32 v[10:11], v[98:99], v[80:81], v[10:11] op_sel:[0,1,0]
	v_pk_fma_f32 v[12:13], v[100:101], v[82:83], v[12:13] op_sel_hi:[1,0,1]
	v_pk_fma_f32 v[8:9], v[102:103], v[82:83], v[8:9] op_sel_hi:[1,0,1]
	v_pk_fma_f32 v[14:15], v[104:105], v[82:83], v[14:15] op_sel_hi:[1,0,1]
	v_pk_fma_f32 v[10:11], v[106:107], v[82:83], v[10:11] op_sel_hi:[1,0,1]
	v_pk_fma_f32 v[12:13], v[108:109], v[82:83], v[12:13] op_sel:[0,1,0]
	v_pk_fma_f32 v[8:9], v[110:111], v[82:83], v[8:9] op_sel:[0,1,0]
	v_pk_fma_f32 v[14:15], v[112:113], v[82:83], v[14:15] op_sel:[0,1,0]
	v_pk_fma_f32 v[10:11], v[114:115], v[82:83], v[10:11] op_sel:[0,1,0]
	global_load_dwordx4 v[80:83], v[20:21], off offset:-8
	v_lshl_add_u64 v[116:117], v[18:19], 0, s[6:7]
	global_load_dwordx4 v[84:87], v[116:117], off
	global_load_dwordx4 v[88:91], v[116:117], off offset:16
	global_load_dwordx4 v[92:95], v[116:117], off offset:512
	global_load_dwordx4 v[96:99], v[116:117], off offset:528
	global_load_dwordx4 v[100:103], v[116:117], off offset:1024
	global_load_dwordx4 v[104:107], v[116:117], off offset:1040
	global_load_dwordx4 v[108:111], v[116:117], off offset:1536
	global_load_dwordx4 v[112:115], v[116:117], off offset:1552
	s_add_u32 s6, s6, 0x800
	s_addc_u32 s7, s7, 0
	v_lshl_add_u64 v[20:21], v[20:21], 0, 16
	s_waitcnt vmcnt(18)
	v_pk_fma_f32 v[12:13], v[148:149], v[144:145], v[12:13] op_sel_hi:[1,0,1]
	v_pk_fma_f32 v[8:9], v[150:151], v[144:145], v[8:9] op_sel_hi:[1,0,1]
	v_pk_fma_f32 v[14:15], v[152:153], v[144:145], v[14:15] op_sel_hi:[1,0,1]
	v_pk_fma_f32 v[10:11], v[154:155], v[144:145], v[10:11] op_sel_hi:[1,0,1]
	v_pk_fma_f32 v[12:13], v[156:157], v[144:145], v[12:13] op_sel:[0,1,0]
	v_pk_fma_f32 v[8:9], v[158:159], v[144:145], v[8:9] op_sel:[0,1,0]
	v_pk_fma_f32 v[14:15], v[160:161], v[144:145], v[14:15] op_sel:[0,1,0]
	v_pk_fma_f32 v[10:11], v[162:163], v[144:145], v[10:11] op_sel:[0,1,0]
	v_pk_fma_f32 v[12:13], v[164:165], v[146:147], v[12:13] op_sel_hi:[1,0,1]
	v_pk_fma_f32 v[8:9], v[166:167], v[146:147], v[8:9] op_sel_hi:[1,0,1]
	v_pk_fma_f32 v[14:15], v[168:169], v[146:147], v[14:15] op_sel_hi:[1,0,1]
	v_pk_fma_f32 v[10:11], v[170:171], v[146:147], v[10:11] op_sel_hi:[1,0,1]
	v_pk_fma_f32 v[12:13], v[172:173], v[146:147], v[12:13] op_sel:[0,1,0]
	v_pk_fma_f32 v[8:9], v[174:175], v[146:147], v[8:9] op_sel:[0,1,0]
	v_pk_fma_f32 v[14:15], v[176:177], v[146:147], v[14:15] op_sel:[0,1,0]
	v_pk_fma_f32 v[10:11], v[178:179], v[146:147], v[10:11] op_sel:[0,1,0]
	global_load_dwordx4 v[144:147], v[20:21], off offset:-8
	v_lshl_add_u64 v[116:117], v[18:19], 0, s[6:7]
	global_load_dwordx4 v[148:151], v[116:117], off
	global_load_dwordx4 v[152:155], v[116:117], off offset:16
	global_load_dwordx4 v[156:159], v[116:117], off offset:512
	global_load_dwordx4 v[160:163], v[116:117], off offset:528
	global_load_dwordx4 v[164:167], v[116:117], off offset:1024
	global_load_dwordx4 v[168:171], v[116:117], off offset:1040
	global_load_dwordx4 v[172:175], v[116:117], off offset:1536
	global_load_dwordx4 v[176:179], v[116:117], off offset:1552
	s_add_u32 s6, s6, 0x800
	s_addc_u32 s7, s7, 0
	v_lshl_add_u64 v[20:21], v[20:21], 0, 16
	s_waitcnt vmcnt(18)
; __device__ __forceinline__ void wcomb_item(const float* w_in, const float* wg, const float* ngain, bf16_t* WinT, int item, int lane) {
;     ...
;     const float* ap = w_in + (size_t)k * DIN + 128 * g; const float* bp = wg + (size_t)g * 128 * 128 + d0;
;     f32x4 c0 = (f32x4){0.f, 0.f, 0.f, 0.f}, c1 = c0;
; #pragma unroll 4
;     for (int cin = 0; cin < 128; ++cin) { const float av = ap[cin]; const f32x4 b0 = *(const f32x4*)(bp + (size_t)cin * 128), b1 = *(const f32x4*)(bp + (size_t)cin * 128 + 4); c0 += b0 * av; c1 += b1 * av; }
	v_pk_fma_f32 v[12:13], v[184:185], v[180:181], v[12:13] op_sel_hi:[1,0,1]
	v_pk_fma_f32 v[8:9], v[186:187], v[180:181], v[8:9] op_sel_hi:[1,0,1]
	v_pk_fma_f32 v[14:15], v[188:189], v[180:181], v[14:15] op_sel_hi:[1,0,1]
	v_pk_fma_f32 v[10:11], v[190:191], v[180:181], v[10:11] op_sel_hi:[1,0,1]
	v_pk_fma_f32 v[12:13], v[192:193], v[180:181], v[12:13] op_sel:[0,1,0]
	v_pk_fma_f32 v[8:9], v[194:195], v[180:181], v[8:9] op_sel:[0,1,0]
	v_pk_fma_f32 v[14:15], v[196:197], v[180:181], v[14:15] op_sel:[0,1,0]
	v_pk_fma_f32 v[10:11], v[198:199], v[180:181], v[10:11] op_sel:[0,1,0]
	v_pk_fma_f32 v[12:13], v[200:201], v[182:183], v[12:13] op_sel_hi:[1,0,1]
	v_pk_fma_f32 v[8:9], v[202:203], v[182:183], v[8:9] op_sel_hi:[1,0,1]
	v_pk_fma_f32 v[14:15], v[204:205], v[182:183], v[14:15] op_sel_hi:[1,0,1]
	v_pk_fma_f32 v[10:11], v[206:207], v[182:183], v[10:11] op_sel_hi:[1,0,1]
	v_pk_fma_f32 v[12:13], v[208:209], v[182:183], v[12:13] op_sel:[0,1,0]
	v_pk_fma_f32 v[8:9], v[210:211], v[182:183], v[8:9] op_sel:[0,1,0]
	v_pk_fma_f32 v[14:15], v[212:213], v[182:183], v[14:15] op_sel:[0,1,0]
	v_pk_fma_f32 v[10:11], v[214:215], v[182:183], v[10:11] op_sel:[0,1,0]
	global_load_dwordx4 v[180:183], v[20:21], off offset:-8
	v_lshl_add_u64 v[116:117], v[18:19], 0, s[6:7]
	global_load_dwordx4 v[184:187], v[116:117], off
	global_load_dwordx4 v[188:191], v[116:117], off offset:16
	global_load_dwordx4 v[192:195], v[116:117], off offset:512
	global_load_dwordx4 v[196:199], v[116:117], off offset:528
	global_load_dwordx4 v[200:203], v[116:117], off offset:1024
	global_load_dwordx4 v[204:207], v[116:117], off offset:1040
	global_load_dwordx4 v[208:211], v[116:117], off offset:1536
	global_load_dwordx4 v[212:215], v[116:117], off offset:1552
	s_add_u32 s6, s6, 0x800
	s_addc_u32 s7, s7, 0
	v_lshl_add_u64 v[20:21], v[20:21], 0, 16
	s_waitcnt vmcnt(18)
	v_pk_fma_f32 v[12:13], v[84:85], v[80:81], v[12:13] op_sel_hi:[1,0,1]
	v_pk_fma_f32 v[8:9], v[86:87], v[80:81], v[8:9] op_sel_hi:[1,0,1]
	v_pk_fma_f32 v[14:15], v[88:89], v[80:81], v[14:15] op_sel_hi:[1,0,1]
	v_pk_fma_f32 v[10:11], v[90:91], v[80:81], v[10:11] op_sel_hi:[1,0,1]
	v_pk_fma_f32 v[12:13], v[92:93], v[80:81], v[12:13] op_sel:[0,1,0]
	v_pk_fma_f32 v[8:9], v[94:95], v[80:81], v[8:9] op_sel:[0,1,0]
	v_pk_fma_f32 v[14:15], v[96:97], v[80:81], v[14:15] op_sel:[0,1,0]
	v_pk_fma_f32 v[10:11], v[98:99], v[80:81], v[10:11] op_sel:[0,1,0]
	v_pk_fma_f32 v[12:13], v[100:101], v[82:83], v[12:13] op_sel_hi:[1,0,1]
	v_pk_fma_f32 v[8:9], v[102:103], v[82:83], v[8:9] op_sel_hi:[1,0,1]
	v_pk_fma_f32 v[14:15], v[104:105], v[82:83], v[14:15] op_sel_hi:[1,0,1]
	v_pk_fma_f32 v[10:11], v[106:107], v[82:83], v[10:11] op_sel_hi:[1,0,1]
	v_pk_fma_f32 v[12:13], v[108:109], v[82:83], v[12:13] op_sel:[0,1,0]
	v_pk_fma_f32 v[8:9], v[110:111], v[82:83], v[8:9] op_sel:[0,1,0]
	v_pk_fma_f32 v[14:15], v[112:113], v[82:83], v[14:15] op_sel:[0,1,0]
	v_pk_fma_f32 v[10:11], v[114:115], v[82:83], v[10:11] op_sel:[0,1,0]
	global_load_dwordx4 v[80:83], v[20:21], off offset:-8
	v_lshl_add_u64 v[116:117], v[18:19], 0, s[6:7]
	global_load_dwordx4 v[84:87], v[116:117], off
	global_load_dwordx4 v[88:91], v[116:117], off offset:16
	global_load_dwordx4 v[92:95], v[116:117], off offset:512
	global_load_dwordx4 v[96:99], v[116:117], off offset:528
	global_load_dwordx4 v[100:103], v[116:117], off offset:1024
	global_load_dwordx4 v[104:107], v[116:117], off offset:1040
	global_load_dwordx4 v[108:111], v[116:117], off offset:1536
	global_load_dwordx4 v[112:115], v[116:117], off offset:1552
	s_add_u32 s6, s6, 0x800
	s_addc_u32 s7, s7, 0
	v_lshl_add_u64 v[20:21], v[20:21], 0, 16
	s_waitcnt vmcnt(18)
	v_pk_fma_f32 v[12:13], v[148:149], v[144:145], v[12:13] op_sel_hi:[1,0,1]
	v_pk_fma_f32 v[8:9], v[150:151], v[144:145], v[8:9] op_sel_hi:[1,0,1]
	v_pk_fma_f32 v[14:15], v[152:153], v[144:145], v[14:15] op_sel_hi:[1,0,1]
	v_pk_fma_f32 v[10:11], v[154:155], v[144:145], v[10:11] op_sel_hi:[1,0,1]
	v_pk_fma_f32 v[12:13], v[156:157], v[144:145], v[12:13] op_sel:[0,1,0]
	v_pk_fma_f32 v[8:9], v[158:159], v[144:145], v[8:9] op_sel:[0,1,0]
	v_pk_fma_f32 v[14:15], v[160:161], v[144:145], v[14:15] op_sel:[0,1,0]
	v_pk_fma_f32 v[10:11], v[162:163], v[144:145], v[10:11] op_sel:[0,1,0]
	v_pk_fma_f32 v[12:13], v[164:165], v[146:147], v[12:13] op_sel_hi:[1,0,1]
	v_pk_fma_f32 v[8:9], v[166:167], v[146:147], v[8:9] op_sel_hi:[1,0,1]
	v_pk_fma_f32 v[14:15], v[168:169], v[146:147], v[14:15] op_sel_hi:[1,0,1]
	v_pk_fma_f32 v[10:11], v[170:171], v[146:147], v[10:11] op_sel_hi:[1,0,1]
	v_pk_fma_f32 v[12:13], v[172:173], v[146:147], v[12:13] op_sel:[0,1,0]
	v_pk_fma_f32 v[8:9], v[174:175], v[146:147], v[8:9] op_sel:[0,1,0]
	v_pk_fma_f32 v[14:15], v[176:177], v[146:147], v[14:15] op_sel:[0,1,0]
	v_pk_fma_f32 v[10:11], v[178:179], v[146:147], v[10:11] op_sel:[0,1,0]
	global_load_dwordx4 v[144:147], v[20:21], off offset:-8
	v_lshl_add_u64 v[116:117], v[18:19], 0, s[6:7]
	global_load_dwordx4 v[148:151], v[116:117], off
	global_load_dwordx4 v[152:155], v[116:117], off offset:16
	global_load_dwordx4 v[156:159], v[116:117], off offset:512
	global_load_dwordx4 v[160:163], v[116:117], off offset:528
	global_load_dwordx4 v[164:167], v[116:117], off offset:1024
	global_load_dwordx4 v[168:171], v[116:117], off offset:1040
	global_load_dwordx4 v[172:175], v[116:117], off offset:1536
	global_load_dwordx4 v[176:179], v[116:117], off offset:1552
	s_add_u32 s6, s6, 0x800
	s_addc_u32 s7, s7, 0
	v_lshl_add_u64 v[20:21], v[20:21], 0, 16
	s_waitcnt vmcnt(18)
; __device__ __forceinline__ unsigned cvt_pk_bf16(float lo, float hi) { unsigned r; asm volatile("v_cvt_pk_bf16_f32 %0, %1, %2" : "=v"(r) : "v"(lo), "v"(hi)); return r; }
; __device__ __forceinline__ void wcomb_item(const float* w_in, const float* wg, const float* ngain, bf16_t* WinT, int item, int lane) {
;     ...
;     for (int cin = 0; cin < 128; ++cin) { const float av = ap[cin]; const f32x4 b0 = *(const f32x4*)(bp + (size_t)cin * 128), b1 = *(const f32x4*)(bp + (size_t)cin * 128 + 4); c0 += b0 * av; c1 += b1 * av; }
;     const float gn = ngain[k];
;     bf16_t* o = WinT + (size_t)(128 * g + d0) * 1024 + k;
; #pragma unroll
;     for (int i = 0; i < 4; ++i) { o[(size_t)i * 1024] = (bf16_t)(cvt_pk_bf16(c0[i] * gn, 0.f) & 0xffffu); o[(size_t)(4 + i) * 1024] = (bf16_t)(cvt_pk_bf16(c1[i] * gn, 0.f) & 0xffffu); }
	v_pk_fma_f32 v[12:13], v[184:185], v[180:181], v[12:13] op_sel_hi:[1,0,1]
	v_pk_fma_f32 v[8:9], v[186:187], v[180:181], v[8:9] op_sel_hi:[1,0,1]
	v_pk_fma_f32 v[14:15], v[188:189], v[180:181], v[14:15] op_sel_hi:[1,0,1]
	v_pk_fma_f32 v[10:11], v[190:191], v[180:181], v[10:11] op_sel_hi:[1,0,1]
	v_pk_fma_f32 v[12:13], v[192:193], v[180:181], v[12:13] op_sel:[0,1,0]
	v_pk_fma_f32 v[8:9], v[194:195], v[180:181], v[8:9] op_sel:[0,1,0]
	v_pk_fma_f32 v[14:15], v[196:197], v[180:181], v[14:15] op_sel:[0,1,0]
	v_pk_fma_f32 v[10:11], v[198:199], v[180:181], v[10:11] op_sel:[0,1,0]
	v_pk_fma_f32 v[12:13], v[200:201], v[182:183], v[12:13] op_sel_hi:[1,0,1]
	v_pk_fma_f32 v[8:9], v[202:203], v[182:183], v[8:9] op_sel_hi:[1,0,1]
	v_pk_fma_f32 v[14:15], v[204:205], v[182:183], v[14:15] op_sel_hi:[1,0,1]
	v_pk_fma_f32 v[10:11], v[206:207], v[182:183], v[10:11] op_sel_hi:[1,0,1]
	v_pk_fma_f32 v[12:13], v[208:209], v[182:183], v[12:13] op_sel:[0,1,0]
	v_pk_fma_f32 v[8:9], v[210:211], v[182:183], v[8:9] op_sel:[0,1,0]
	v_pk_fma_f32 v[14:15], v[212:213], v[182:183], v[14:15] op_sel:[0,1,0]
	v_pk_fma_f32 v[10:11], v[214:215], v[182:183], v[10:11] op_sel:[0,1,0]
	s_waitcnt vmcnt(9)
	v_pk_fma_f32 v[12:13], v[84:85], v[80:81], v[12:13] op_sel_hi:[1,0,1]
	v_pk_fma_f32 v[8:9], v[86:87], v[80:81], v[8:9] op_sel_hi:[1,0,1]
	v_pk_fma_f32 v[14:15], v[88:89], v[80:81], v[14:15] op_sel_hi:[1,0,1]
	v_pk_fma_f32 v[10:11], v[90:91], v[80:81], v[10:11] op_sel_hi:[1,0,1]
	v_pk_fma_f32 v[12:13], v[92:93], v[80:81], v[12:13] op_sel:[0,1,0]
	v_pk_fma_f32 v[8:9], v[94:95], v[80:81], v[8:9] op_sel:[0,1,0]
	v_pk_fma_f32 v[14:15], v[96:97], v[80:81], v[14:15] op_sel:[0,1,0]
	v_pk_fma_f32 v[10:11], v[98:99], v[80:81], v[10:11] op_sel:[0,1,0]
	v_pk_fma_f32 v[12:13], v[100:101], v[82:83], v[12:13] op_sel_hi:[1,0,1]
	v_pk_fma_f32 v[8:9], v[102:103], v[82:83], v[8:9] op_sel_hi:[1,0,1]
	v_pk_fma_f32 v[14:15], v[104:105], v[82:83], v[14:15] op_sel_hi:[1,0,1]
	v_pk_fma_f32 v[10:11], v[106:107], v[82:83], v[10:11] op_sel_hi:[1,0,1]
	v_pk_fma_f32 v[12:13], v[108:109], v[82:83], v[12:13] op_sel:[0,1,0]
	v_pk_fma_f32 v[8:9], v[110:111], v[82:83], v[8:9] op_sel:[0,1,0]
	v_pk_fma_f32 v[14:15], v[112:113], v[82:83], v[14:15] op_sel:[0,1,0]
	v_pk_fma_f32 v[10:11], v[114:115], v[82:83], v[10:11] op_sel:[0,1,0]
	s_waitcnt vmcnt(0)
	v_pk_fma_f32 v[12:13], v[148:149], v[144:145], v[12:13] op_sel_hi:[1,0,1]
	v_pk_fma_f32 v[8:9], v[150:151], v[144:145], v[8:9] op_sel_hi:[1,0,1]
	v_pk_fma_f32 v[14:15], v[152:153], v[144:145], v[14:15] op_sel_hi:[1,0,1]
	v_pk_fma_f32 v[10:11], v[154:155], v[144:145], v[10:11] op_sel_hi:[1,0,1]
	v_pk_fma_f32 v[12:13], v[156:157], v[144:145], v[12:13] op_sel:[0,1,0]
	v_pk_fma_f32 v[8:9], v[158:159], v[144:145], v[8:9] op_sel:[0,1,0]
	v_pk_fma_f32 v[14:15], v[160:161], v[144:145], v[14:15] op_sel:[0,1,0]
	v_pk_fma_f32 v[10:11], v[162:163], v[144:145], v[10:11] op_sel:[0,1,0]
	v_pk_fma_f32 v[12:13], v[164:165], v[146:147], v[12:13] op_sel_hi:[1,0,1]
	v_pk_fma_f32 v[8:9], v[166:167], v[146:147], v[8:9] op_sel_hi:[1,0,1]
	v_pk_fma_f32 v[14:15], v[168:169], v[146:147], v[14:15] op_sel_hi:[1,0,1]
	v_pk_fma_f32 v[10:11], v[170:171], v[146:147], v[10:11] op_sel_hi:[1,0,1]
	v_pk_fma_f32 v[12:13], v[172:173], v[146:147], v[12:13] op_sel:[0,1,0]
	v_pk_fma_f32 v[8:9], v[174:175], v[146:147], v[8:9] op_sel:[0,1,0]
	v_pk_fma_f32 v[14:15], v[176:177], v[146:147], v[14:15] op_sel:[0,1,0]
	v_pk_fma_f32 v[10:11], v[178:179], v[146:147], v[10:11] op_sel:[0,1,0]
	v_readlane_b32 s48, v253, 61
	v_lshlrev_b32_e32 v0, 2, v22
	v_readlane_b32 s54, v254, 3
	v_readlane_b32 s55, v254, 4
	v_or_b32_e32 v18, s0, v23
	v_ashrrev_i32_e32 v19, 31, v18
	v_lshlrev_b64 v[18:19], 11, v[18:19]
	v_lshl_add_u64 v[18:19], s[4:5], 0, v[18:19]
	s_movk_i32 s0, 0x2000
	global_load_dword v26, v0, s[54:55]
	v_lshlrev_b32_e32 v0, 1, v22
	v_lshl_add_u64 v[18:19], v[18:19], 0, v[0:1]
	v_add_co_u32_e32 v20, vcc, s0, v18
	s_mov_b64 s[0:1], vcc
	v_addc_co_u32_e64 v21, s[0:1], 0, v19, s[0:1]
	v_add_co_u32_e32 v22, vcc, s98, v18
	s_mov_b64 s[0:1], vcc
	v_add_co_u32_e32 v24, vcc, 0x3000, v18
	v_addc_co_u32_e64 v23, s[0:1], 0, v19, s[0:1]
	s_nop 0
	v_addc_co_u32_e32 v25, vcc, 0, v19, vcc
	v_readlane_b32 s49, v253, 62
	v_readlane_b32 s50, v253, 63
	v_readlane_b32 s51, v254, 0
	v_readlane_b32 s52, v254, 1
	v_readlane_b32 s53, v254, 2
	v_readlane_b32 s56, v254, 5
	v_readlane_b32 s57, v254, 6
	v_readlane_b32 s58, v254, 7
	v_readlane_b32 s59, v254, 8
	v_readlane_b32 s60, v254, 9
	v_readlane_b32 s61, v254, 10
	v_readlane_b32 s62, v254, 11
	v_readlane_b32 s63, v254, 12
	s_waitcnt vmcnt(0)
	v_mul_f32_e32 v0, v12, v26
	v_cvt_pk_bf16_f32 v0, v0, v1
	v_mul_f32_e32 v12, v14, v26
	global_store_short v[18:19], v0, off
	v_cvt_pk_bf16_f32 v0, v12, v1
	v_mul_f32_e32 v13, v13, v26
	global_store_short v[20:21], v0, off
	v_cvt_pk_bf16_f32 v0, v13, v1
	v_mul_f32_e32 v14, v15, v26
	global_store_short v[18:19], v0, off offset:2048
	v_cvt_pk_bf16_f32 v0, v14, v1
	v_mul_f32_e32 v8, v8, v26
	global_store_short v[20:21], v0, off offset:2048
	v_cvt_pk_bf16_f32 v0, v8, v1
	v_mul_f32_e32 v10, v10, v26
	global_store_short v[22:23], v0, off
	v_cvt_pk_bf16_f32 v0, v10, v1
	v_mul_f32_e32 v9, v9, v26
	global_store_short v[24:25], v0, off
	v_cvt_pk_bf16_f32 v0, v9, v1
	v_mul_f32_e32 v11, v11, v26
	global_store_short v[22:23], v0, off offset:2048
	v_cvt_pk_bf16_f32 v0, v11, v1
	global_store_short v[24:25], v0, off offset:2048
	s_branch .LBB0_782
